# stacked small edits: epilogue weights by LDS-DMA at gather start, V-loop pair reads one iteration early, hand-scheduled sample V half, packed-f32 epilogue dots
# baseline (speedup 1.0000x reference)
;     DEVI int* eidx() const { return (int*)(ws + WS_EIDX); }
;     ...
;     int e[NTL]; float g[NTL], s_u[NTL], s_v[NTL];
; #pragma unroll
;     for (int t = 0; t < NTL; ++t) { e[t] = eidx[(size_t)r * 128 + (tbase + t) * 16 + n16]; g[t] = gwv[(size_t)r * 128 + (tbase + t) * 16 + n16]; }
; #pragma unroll
;     for (int t = 0; t < NTL; ++t) { s_u[t] = su[e[t]]; s_v[t] = sv[e[t]]; }
;     const unsigned char* up[NTL];
; #pragma unroll
;     for (int t = 0; t < NTL; ++t) up[t] = u8 + (size_t)e[t] * D + kq * 16;
;     const unsigned char* hp = h8 + (n16 < 8 ? (size_t)0 : (size_t)M * D) + (size_t)r * D + kq * 16;
;     f32x4_t acc[NTL];
; #pragma unroll
;     for (int t = 0; t < NTL; ++t) acc[t] = (f32x4_t){0.f, 0.f, 0.f, 0.f};
;     u32x4_t b0[NTL], b1[NTL];
; #pragma unroll
;     for (int t = 0; t < NTL; ++t) { b0[t] = *(const u32x4_t*)(up[t]); b1[t] = *(const u32x4_t*)(up[t] + 64); }
.LBB0_1084:
	s_or_b64 exec, exec, s[40:41]
	v_readlane_b32 s2, v253, 41
	s_mov_b64 s[6:7], s[74:75]
	s_mov_b64 s[4:5], s[72:73]
	s_mov_b32 s8, s2
	v_mov_b32_e32 v1, v210
	v_readlane_b32 s48, v252, 3
	s_mov_b32 s36, s68
	s_waitcnt lgkmcnt(0)
	s_barrier
	s_cmpk_gt_i32 s48, 0x3fff
	v_and_b32_e32 v116, 15, v1
	v_and_b32_e32 v102, -16, v1
	v_lshlrev_b32_e32 v100, 4, v1
	v_cmp_gt_u32_e64 s[2:3], 16, v1
	s_mul_hi_i32 s46, s8, 0x6c000
	s_mul_i32 s47, s8, 0x6c000
	v_ashrrev_i32_e32 v103, 31, v102
	v_cmp_gt_u32_e32 vcc, 8, v116
	v_lshl_add_u32 v117, v1, 3, s85
	v_ashrrev_i32_e32 v101, 31, v100
	s_cbranch_scc1 .LBB0_1124
	s_add_u32 s9, s8, 1
	s_mul_i32 s9, s9, 0xc000
	s_add_u32 s10, s6, 0x1f812100
	s_addc_u32 s11, s7, 0
	s_add_u32 s10, s10, s9
	s_addc_u32 s11, s11, 0
	s_lshr_b32 s12, s85, 13
	s_mul_i32 s12, s12, 0x1800
	s_add_u32 s10, s10, s12
	s_addc_u32 s11, s11, 0
	v_lshlrev_b32_e32 v2, 4, v1
	v_mov_b32_e32 v3, 0
	v_lshl_add_u64 v[2:3], s[10:11], 0, v[2:3]
	s_add_u32 s13, s12, 0x14100
	s_mov_b32 m0, s13
	s_nop 0
	global_load_lds_dwordx4 v[2:3], off
	global_load_lds_dwordx4 v[2:3], off offset:1024
	global_load_lds_dwordx4 v[2:3], off offset:2048
	global_load_lds_dwordx4 v[2:3], off offset:3072
	s_mov_b64 s[10:11], 0x1000
	v_lshl_add_u64 v[2:3], v[2:3], 0, s[10:11]
	s_add_u32 s13, s13, 0x1000
	s_mov_b32 m0, s13
	s_nop 0
	global_load_lds_dwordx4 v[2:3], off
	global_load_lds_dwordx4 v[2:3], off offset:1024
	s_lshl_b32 s20, s34, 9
	s_lshl_b32 s21, s34, 10
	s_lshl_b32 s11, s8, 24
	s_add_u32 s56, s6, 0x1fa42100
	s_addc_u32 s57, s7, 0
	s_add_u32 s56, s56, s11
	s_addc_u32 s57, s57, 0
	s_mov_b32 s12, s56
	s_mov_b32 s13, s57
	s_lshl_b32 s11, s48, 9
	s_add_u32 s58, s6, 0x1b292100
	s_addc_u32 s59, s7, 0
	s_add_u32 s58, s58, s11
	s_addc_u32 s59, s59, 0
	s_lshl_b32 s11, s48, 10
	s_add_u32 s60, s6, 0x2fac2100
	s_addc_u32 s61, s7, 0
	s_add_u32 s60, s60, s11
	s_addc_u32 s61, s61, 0
	s_mov_b32 s40, 0xaaaaaaaa
	s_mov_b32 s41, 0xaaaaaaaa
	s_mov_b32 s42, 0xcccccccc
	s_mov_b32 s43, 0xcccccccc
	v_and_b32_e32 v2, 7, v1
	v_lshrrev_b32_e32 v3, 3, v1
	v_lshlrev_b32_e32 v4, 4, v2
	v_lshlrev_b32_e32 v5, 6, v3
	v_lshlrev_b32_e32 v6, 7, v3
	v_add3_u32 v6, v6, v4, s85
	v_mov_b32_e32 v8, 0x3d000000
	v_mov_b32_e32 v9, 0x3d000000
	v_mov_b32_e32 v118, 0
	v_mov_b32_e32 v119, 0
	ds_write_b32 v6, v118 offset:4
	ds_write_b32 v6, v118 offset:12
	ds_write_b32 v6, v118 offset:1028
	ds_write_b32 v6, v118 offset:1036
	ds_write_b32 v6, v118 offset:2052
	ds_write_b32 v6, v118 offset:2060
	ds_write_b32 v6, v118 offset:3076
	ds_write_b32 v6, v118 offset:3084
	ds_write_b32 v6, v118 offset:4100
	ds_write_b32 v6, v118 offset:4108
	ds_write_b32 v6, v118 offset:5124
	ds_write_b32 v6, v118 offset:5132
	ds_write_b32 v6, v118 offset:6148
	ds_write_b32 v6, v118 offset:6156
	ds_write_b32 v6, v118 offset:7172
	ds_write_b32 v6, v118 offset:7180
	global_load_dwordx4 v[84:87], v5, s[58:59] offset:0
	global_load_dwordx4 v[88:91], v5, s[58:59] offset:16
	global_load_dwordx4 v[92:95], v5, s[58:59] offset:32
	global_load_dwordx4 v[96:99], v5, s[58:59] offset:48
	s_waitcnt vmcnt(0)
	v_lshl_add_u32 v68, v84, 10, v4
	v_lshl_add_u32 v69, v85, 10, v4
	v_lshl_add_u32 v70, v86, 10, v4
	v_lshl_add_u32 v71, v87, 10, v4
	v_lshl_add_u32 v72, v88, 10, v4
	v_lshl_add_u32 v73, v89, 10, v4
	v_lshl_add_u32 v74, v90, 10, v4
	v_lshl_add_u32 v75, v91, 10, v4
	v_lshl_add_u32 v76, v92, 10, v4
	v_lshl_add_u32 v77, v93, 10, v4
	v_lshl_add_u32 v78, v94, 10, v4
	v_lshl_add_u32 v79, v95, 10, v4
	v_lshl_add_u32 v80, v96, 10, v4
	v_lshl_add_u32 v81, v97, 10, v4
	v_lshl_add_u32 v82, v98, 10, v4
	v_lshl_add_u32 v83, v99, 10, v4
	s_add_u32 s18, s60, 0x1100000
	s_addc_u32 s19, s61, 0
	global_load_dwordx4 v[180:183], v4, s[60:61]
	global_load_dwordx4 v[184:187], v4, s[18:19]
	s_add_u32 s14, s58, s20
	s_addc_u32 s15, s59, 0
	global_load_dwordx4 v[84:87], v5, s[14:15] offset:0
	global_load_dwordx4 v[88:91], v5, s[14:15] offset:16
	global_load_dwordx4 v[92:95], v5, s[14:15] offset:32
	global_load_dwordx4 v[96:99], v5, s[14:15] offset:48
	global_load_dwordx4 v[120:123], v68, s[12:13]
	global_load_dwordx4 v[124:127], v69, s[12:13]
	global_load_dwordx4 v[128:131], v70, s[12:13]
	global_load_dwordx4 v[132:135], v71, s[12:13]
	global_load_dwordx4 v[136:139], v72, s[12:13]
	global_load_dwordx4 v[140:143], v73, s[12:13]
	global_load_dwordx4 v[144:147], v74, s[12:13]
	global_load_dwordx4 v[148:151], v75, s[12:13]
	global_load_dwordx4 v[152:155], v76, s[12:13]
	global_load_dwordx4 v[156:159], v77, s[12:13]
	global_load_dwordx4 v[160:163], v78, s[12:13]
	global_load_dwordx4 v[164:167], v79, s[12:13]
	global_load_dwordx4 v[168:171], v80, s[12:13]
	global_load_dwordx4 v[172:175], v81, s[12:13]
	global_load_dwordx4 v[188:191], v82, s[12:13]
	global_load_dwordx4 v[192:195], v83, s[12:13]
	s_mov_b32 s22, 0

; DEVI float gelu_f(float x) { const float u = 0.7978845608028654f * (x + 0.044715f * x * x * x); return x * __builtin_amdgcn_rcpf(1.f + __expf(-2.f * u)); }
;     ...
;     for (int t = 0; t < NTL; ++t) { b0[t] = *(const u32x4_t*)(up[t]); b1[t] = *(const u32x4_t*)(up[t] + 64); }
;     ...
;     for (int m = 0; m < 16; m += 2) {
;         const u32x4_t a0 = *(const u32x4_t*)(hp + m * 64), a1 = *(const u32x4_t*)(hp + m * 64 + 64);
; #pragma unroll
;         for (int t = 0; t < NTL; ++t) FP8MM(a0, b0[t], acc[t]);
;         if (m + 2 < 16) {
; #pragma unroll
;             for (int t = 0; t < NTL; ++t) b0[t] = *(const u32x4_t*)(up[t] + (m + 2) * 64);
;         }
; #pragma unroll
;         for (int t = 0; t < NTL; ++t) FP8MM(a1, b1[t], acc[t]);
;         if (m + 3 < 16) {
; #pragma unroll
;             for (int t = 0; t < NTL; ++t) b1[t] = *(const u32x4_t*)(up[t] + (m + 3) * 64);
;         }
;     }
;     ...
; #pragma unroll
;     for (int t = 0; t < NTL; ++t) { const float lo = __shfl_xor(acc[t][0], 32); const float dot = (acc[t][0] + lo * (1.f / 32.f)) * s_u[t];
;         if (kq == 0) pl[t * 16 + n16] = (u32x2_t){(unsigned)e[t], __float_as_uint(g[t] * gelu_f(dot) * s_v[t])}; }
.Lg1_nobar:
	s_waitcnt vmcnt(16)
	v_cvt_pk_f32_fp8_e32 v[10:11], v180
	v_cvt_pk_f32_fp8_sdwa v[12:13], v180 src0_sel:WORD_1
	v_cvt_pk_f32_fp8_e32 v[14:15], v181
	v_cvt_pk_f32_fp8_sdwa v[16:17], v181 src0_sel:WORD_1
	v_cvt_pk_f32_fp8_e32 v[18:19], v182
	v_cvt_pk_f32_fp8_sdwa v[20:21], v182 src0_sel:WORD_1
	v_cvt_pk_f32_fp8_e32 v[22:23], v183
	v_cvt_pk_f32_fp8_sdwa v[24:25], v183 src0_sel:WORD_1
	v_cvt_pk_f32_fp8_e32 v[26:27], v184
	v_cvt_pk_f32_fp8_sdwa v[28:29], v184 src0_sel:WORD_1
	v_cvt_pk_f32_fp8_e32 v[30:31], v185
	v_cvt_pk_f32_fp8_sdwa v[32:33], v185 src0_sel:WORD_1
	v_cvt_pk_f32_fp8_e32 v[34:35], v186
	v_cvt_pk_f32_fp8_sdwa v[36:37], v186 src0_sel:WORD_1
	v_cvt_pk_f32_fp8_e32 v[38:39], v187
	v_cvt_pk_f32_fp8_sdwa v[40:41], v187 src0_sel:WORD_1
	v_pk_fma_f32 v[10:11], v[26:27], v[8:9], v[10:11]
	v_pk_fma_f32 v[12:13], v[28:29], v[8:9], v[12:13]
	v_pk_fma_f32 v[14:15], v[30:31], v[8:9], v[14:15]
	v_pk_fma_f32 v[16:17], v[32:33], v[8:9], v[16:17]
	v_pk_fma_f32 v[18:19], v[34:35], v[8:9], v[18:19]
	v_pk_fma_f32 v[20:21], v[36:37], v[8:9], v[20:21]
	v_pk_fma_f32 v[22:23], v[38:39], v[8:9], v[22:23]
	v_pk_fma_f32 v[24:25], v[40:41], v[8:9], v[24:25]
	v_lshl_add_u32 v68, v84, 10, v4
	v_lshl_add_u32 v69, v85, 10, v4
	v_lshl_add_u32 v70, v86, 10, v4
	v_lshl_add_u32 v71, v87, 10, v4
	v_lshl_add_u32 v72, v88, 10, v4
	v_lshl_add_u32 v73, v89, 10, v4
	v_lshl_add_u32 v74, v90, 10, v4
	v_lshl_add_u32 v75, v91, 10, v4
	v_lshl_add_u32 v76, v92, 10, v4
	v_lshl_add_u32 v77, v93, 10, v4
	v_lshl_add_u32 v78, v94, 10, v4
	v_lshl_add_u32 v79, v95, 10, v4
	v_lshl_add_u32 v80, v96, 10, v4
	v_lshl_add_u32 v81, v97, 10, v4
	v_lshl_add_u32 v82, v98, 10, v4
	v_lshl_add_u32 v83, v99, 10, v4
	s_add_u32 s9, s22, 1
	s_and_b32 s10, s9, 7
	s_lshr_b32 s11, s9, 3
	s_mul_i32 s23, s10, s21
	s_lshl_b32 s11, s11, 7
	s_add_u32 s16, s60, s23
	s_addc_u32 s17, s61, 0
	s_add_u32 s16, s16, s11
	s_addc_u32 s17, s17, 0
	s_add_u32 s18, s16, 0x1100000
	s_addc_u32 s19, s17, 0
	s_add_u32 s12, s56, s11
	s_addc_u32 s13, s57, 0
	s_add_u32 s9, s22, 2
	s_and_b32 s9, s9, 7
	s_mul_i32 s9, s9, s20
	s_add_u32 s14, s58, s9
	s_addc_u32 s15, s59, 0
	global_load_dwordx4 v[180:183], v4, s[16:17]
	global_load_dwordx4 v[184:187], v4, s[18:19]
	global_load_dwordx4 v[84:87], v5, s[14:15] offset:0
	global_load_dwordx4 v[88:91], v5, s[14:15] offset:16
	global_load_dwordx4 v[92:95], v5, s[14:15] offset:32
	global_load_dwordx4 v[96:99], v5, s[14:15] offset:48
	s_waitcnt vmcnt(20)
	v_cvt_pk_f32_fp8_e32 v[26:27], v120
	v_cvt_pk_f32_fp8_sdwa v[28:29], v120 src0_sel:WORD_1
	v_cvt_pk_f32_fp8_e32 v[30:31], v121
	v_cvt_pk_f32_fp8_sdwa v[32:33], v121 src0_sel:WORD_1
	v_cvt_pk_f32_fp8_e32 v[34:35], v122
	v_cvt_pk_f32_fp8_sdwa v[36:37], v122 src0_sel:WORD_1
	v_cvt_pk_f32_fp8_e32 v[38:39], v123
	v_cvt_pk_f32_fp8_sdwa v[40:41], v123 src0_sel:WORD_1
	v_cvt_pk_f32_fp8_e32 v[42:43], v124
	v_cvt_pk_f32_fp8_sdwa v[44:45], v124 src0_sel:WORD_1
	v_cvt_pk_f32_fp8_e32 v[46:47], v125
	v_cvt_pk_f32_fp8_sdwa v[48:49], v125 src0_sel:WORD_1
	v_cvt_pk_f32_fp8_e32 v[50:51], v126
	v_cvt_pk_f32_fp8_sdwa v[52:53], v126 src0_sel:WORD_1
	v_cvt_pk_f32_fp8_e32 v[54:55], v127
	v_cvt_pk_f32_fp8_sdwa v[56:57], v127 src0_sel:WORD_1
	global_load_dwordx4 v[120:123], v68, s[12:13]
	global_load_dwordx4 v[124:127], v69, s[12:13]
	v_pk_mul_f32 v[58:59], v[26:27], v[10:11]
	v_pk_mul_f32 v[60:61], v[42:43], v[10:11]
	v_pk_fma_f32 v[58:59], v[28:29], v[12:13], v[58:59]
	v_pk_fma_f32 v[60:61], v[44:45], v[12:13], v[60:61]
	v_pk_fma_f32 v[58:59], v[30:31], v[14:15], v[58:59]
	v_pk_fma_f32 v[60:61], v[46:47], v[14:15], v[60:61]
	v_pk_fma_f32 v[58:59], v[32:33], v[16:17], v[58:59]
	v_pk_fma_f32 v[60:61], v[48:49], v[16:17], v[60:61]
	v_pk_fma_f32 v[58:59], v[34:35], v[18:19], v[58:59]
	v_pk_fma_f32 v[60:61], v[50:51], v[18:19], v[60:61]
	v_pk_fma_f32 v[58:59], v[36:37], v[20:21], v[58:59]
	v_pk_fma_f32 v[60:61], v[52:53], v[20:21], v[60:61]
	v_pk_fma_f32 v[58:59], v[38:39], v[22:23], v[58:59]
	v_pk_fma_f32 v[60:61], v[54:55], v[22:23], v[60:61]
	v_pk_fma_f32 v[58:59], v[40:41], v[24:25], v[58:59]
	v_pk_fma_f32 v[60:61], v[56:57], v[24:25], v[60:61]
	v_add_f32_e32 v104, v58, v59
	v_add_f32_e32 v105, v60, v61
	s_waitcnt vmcnt(20)
	v_cvt_pk_f32_fp8_e32 v[26:27], v128
	v_cvt_pk_f32_fp8_sdwa v[28:29], v128 src0_sel:WORD_1
	v_cvt_pk_f32_fp8_e32 v[30:31], v129
	v_cvt_pk_f32_fp8_sdwa v[32:33], v129 src0_sel:WORD_1
	v_cvt_pk_f32_fp8_e32 v[34:35], v130
	v_cvt_pk_f32_fp8_sdwa v[36:37], v130 src0_sel:WORD_1
	v_cvt_pk_f32_fp8_e32 v[38:39], v131
	v_cvt_pk_f32_fp8_sdwa v[40:41], v131 src0_sel:WORD_1
	v_cvt_pk_f32_fp8_e32 v[42:43], v132
	v_cvt_pk_f32_fp8_sdwa v[44:45], v132 src0_sel:WORD_1
	v_cvt_pk_f32_fp8_e32 v[46:47], v133
	v_cvt_pk_f32_fp8_sdwa v[48:49], v133 src0_sel:WORD_1
	v_cvt_pk_f32_fp8_e32 v[50:51], v134
	v_cvt_pk_f32_fp8_sdwa v[52:53], v134 src0_sel:WORD_1
	v_cvt_pk_f32_fp8_e32 v[54:55], v135
	v_cvt_pk_f32_fp8_sdwa v[56:57], v135 src0_sel:WORD_1
	global_load_dwordx4 v[128:131], v70, s[12:13]
	global_load_dwordx4 v[132:135], v71, s[12:13]
	v_pk_mul_f32 v[58:59], v[26:27], v[10:11]
	v_pk_mul_f32 v[60:61], v[42:43], v[10:11]
	v_pk_fma_f32 v[58:59], v[28:29], v[12:13], v[58:59]
	v_pk_fma_f32 v[60:61], v[44:45], v[12:13], v[60:61]
	v_pk_fma_f32 v[58:59], v[30:31], v[14:15], v[58:59]
	v_pk_fma_f32 v[60:61], v[46:47], v[14:15], v[60:61]
	v_pk_fma_f32 v[58:59], v[32:33], v[16:17], v[58:59]
	v_pk_fma_f32 v[60:61], v[48:49], v[16:17], v[60:61]
	v_pk_fma_f32 v[58:59], v[34:35], v[18:19], v[58:59]
	v_pk_fma_f32 v[60:61], v[50:51], v[18:19], v[60:61]
	v_pk_fma_f32 v[58:59], v[36:37], v[20:21], v[58:59]
	v_pk_fma_f32 v[60:61], v[52:53], v[20:21], v[60:61]
	v_pk_fma_f32 v[58:59], v[38:39], v[22:23], v[58:59]
	v_pk_fma_f32 v[60:61], v[54:55], v[22:23], v[60:61]
	v_pk_fma_f32 v[58:59], v[40:41], v[24:25], v[58:59]
	v_pk_fma_f32 v[60:61], v[56:57], v[24:25], v[60:61]
	v_add_f32_e32 v106, v58, v59
	v_add_f32_e32 v107, v60, v61
	s_waitcnt vmcnt(20)
;     ...
;     for (int t = 0; t < NTL; ++t) { b0[t] = *(const u32x4_t*)(up[t]); b1[t] = *(const u32x4_t*)(up[t] + 64); }
;     ...
;     for (int m = 0; m < 16; m += 2) {
;         const u32x4_t a0 = *(const u32x4_t*)(hp + m * 64), a1 = *(const u32x4_t*)(hp + m * 64 + 64);
; #pragma unroll
;         for (int t = 0; t < NTL; ++t) FP8MM(a0, b0[t], acc[t]);
;         if (m + 2 < 16) {
; #pragma unroll
;             for (int t = 0; t < NTL; ++t) b0[t] = *(const u32x4_t*)(up[t] + (m + 2) * 64);
;         }
; #pragma unroll
;         for (int t = 0; t < NTL; ++t) FP8MM(a1, b1[t], acc[t]);
;         if (m + 3 < 16) {
; #pragma unroll
;             for (int t = 0; t < NTL; ++t) b1[t] = *(const u32x4_t*)(up[t] + (m + 3) * 64);
;         }
;     }
	v_cvt_pk_f32_fp8_e32 v[26:27], v136
	v_cvt_pk_f32_fp8_sdwa v[28:29], v136 src0_sel:WORD_1
	v_cvt_pk_f32_fp8_e32 v[30:31], v137
	v_cvt_pk_f32_fp8_sdwa v[32:33], v137 src0_sel:WORD_1
	v_cvt_pk_f32_fp8_e32 v[34:35], v138
	v_cvt_pk_f32_fp8_sdwa v[36:37], v138 src0_sel:WORD_1
	v_cvt_pk_f32_fp8_e32 v[38:39], v139
	v_cvt_pk_f32_fp8_sdwa v[40:41], v139 src0_sel:WORD_1
	v_cvt_pk_f32_fp8_e32 v[42:43], v140
	v_cvt_pk_f32_fp8_sdwa v[44:45], v140 src0_sel:WORD_1
	v_cvt_pk_f32_fp8_e32 v[46:47], v141
	v_cvt_pk_f32_fp8_sdwa v[48:49], v141 src0_sel:WORD_1
	v_cvt_pk_f32_fp8_e32 v[50:51], v142
	v_cvt_pk_f32_fp8_sdwa v[52:53], v142 src0_sel:WORD_1
	v_cvt_pk_f32_fp8_e32 v[54:55], v143
	v_cvt_pk_f32_fp8_sdwa v[56:57], v143 src0_sel:WORD_1
	global_load_dwordx4 v[136:139], v72, s[12:13]
	global_load_dwordx4 v[140:143], v73, s[12:13]
	v_pk_mul_f32 v[58:59], v[26:27], v[10:11]
	v_pk_mul_f32 v[60:61], v[42:43], v[10:11]
	v_pk_fma_f32 v[58:59], v[28:29], v[12:13], v[58:59]
	v_pk_fma_f32 v[60:61], v[44:45], v[12:13], v[60:61]
	v_pk_fma_f32 v[58:59], v[30:31], v[14:15], v[58:59]
	v_pk_fma_f32 v[60:61], v[46:47], v[14:15], v[60:61]
	v_pk_fma_f32 v[58:59], v[32:33], v[16:17], v[58:59]
	v_pk_fma_f32 v[60:61], v[48:49], v[16:17], v[60:61]
	v_pk_fma_f32 v[58:59], v[34:35], v[18:19], v[58:59]
	v_pk_fma_f32 v[60:61], v[50:51], v[18:19], v[60:61]
	v_pk_fma_f32 v[58:59], v[36:37], v[20:21], v[58:59]
	v_pk_fma_f32 v[60:61], v[52:53], v[20:21], v[60:61]
	v_pk_fma_f32 v[58:59], v[38:39], v[22:23], v[58:59]
	v_pk_fma_f32 v[60:61], v[54:55], v[22:23], v[60:61]
	v_pk_fma_f32 v[58:59], v[40:41], v[24:25], v[58:59]
	v_pk_fma_f32 v[60:61], v[56:57], v[24:25], v[60:61]
	v_add_f32_e32 v108, v58, v59
	v_add_f32_e32 v109, v60, v61
	s_waitcnt vmcnt(20)
	v_cvt_pk_f32_fp8_e32 v[26:27], v144
	v_cvt_pk_f32_fp8_sdwa v[28:29], v144 src0_sel:WORD_1
	v_cvt_pk_f32_fp8_e32 v[30:31], v145
	v_cvt_pk_f32_fp8_sdwa v[32:33], v145 src0_sel:WORD_1
	v_cvt_pk_f32_fp8_e32 v[34:35], v146
	v_cvt_pk_f32_fp8_sdwa v[36:37], v146 src0_sel:WORD_1
	v_cvt_pk_f32_fp8_e32 v[38:39], v147
	v_cvt_pk_f32_fp8_sdwa v[40:41], v147 src0_sel:WORD_1
	v_cvt_pk_f32_fp8_e32 v[42:43], v148
	v_cvt_pk_f32_fp8_sdwa v[44:45], v148 src0_sel:WORD_1
	v_cvt_pk_f32_fp8_e32 v[46:47], v149
	v_cvt_pk_f32_fp8_sdwa v[48:49], v149 src0_sel:WORD_1
	v_cvt_pk_f32_fp8_e32 v[50:51], v150
	v_cvt_pk_f32_fp8_sdwa v[52:53], v150 src0_sel:WORD_1
	v_cvt_pk_f32_fp8_e32 v[54:55], v151
	v_cvt_pk_f32_fp8_sdwa v[56:57], v151 src0_sel:WORD_1
	global_load_dwordx4 v[144:147], v74, s[12:13]
	global_load_dwordx4 v[148:151], v75, s[12:13]
	v_pk_mul_f32 v[58:59], v[26:27], v[10:11]
	v_pk_mul_f32 v[60:61], v[42:43], v[10:11]
	v_pk_fma_f32 v[58:59], v[28:29], v[12:13], v[58:59]
	v_pk_fma_f32 v[60:61], v[44:45], v[12:13], v[60:61]
	v_pk_fma_f32 v[58:59], v[30:31], v[14:15], v[58:59]
	v_pk_fma_f32 v[60:61], v[46:47], v[14:15], v[60:61]
	v_pk_fma_f32 v[58:59], v[32:33], v[16:17], v[58:59]
	v_pk_fma_f32 v[60:61], v[48:49], v[16:17], v[60:61]
	v_pk_fma_f32 v[58:59], v[34:35], v[18:19], v[58:59]
	v_pk_fma_f32 v[60:61], v[50:51], v[18:19], v[60:61]
	v_pk_fma_f32 v[58:59], v[36:37], v[20:21], v[58:59]
	v_pk_fma_f32 v[60:61], v[52:53], v[20:21], v[60:61]
	v_pk_fma_f32 v[58:59], v[38:39], v[22:23], v[58:59]
	v_pk_fma_f32 v[60:61], v[54:55], v[22:23], v[60:61]
	v_pk_fma_f32 v[58:59], v[40:41], v[24:25], v[58:59]
	v_pk_fma_f32 v[60:61], v[56:57], v[24:25], v[60:61]
	v_add_f32_e32 v110, v58, v59
	v_add_f32_e32 v111, v60, v61
	s_waitcnt vmcnt(20)
	v_cvt_pk_f32_fp8_e32 v[26:27], v152
	v_cvt_pk_f32_fp8_sdwa v[28:29], v152 src0_sel:WORD_1
	v_cvt_pk_f32_fp8_e32 v[30:31], v153
	v_cvt_pk_f32_fp8_sdwa v[32:33], v153 src0_sel:WORD_1
	v_cvt_pk_f32_fp8_e32 v[34:35], v154
	v_cvt_pk_f32_fp8_sdwa v[36:37], v154 src0_sel:WORD_1
	v_cvt_pk_f32_fp8_e32 v[38:39], v155
	v_cvt_pk_f32_fp8_sdwa v[40:41], v155 src0_sel:WORD_1
	v_cvt_pk_f32_fp8_e32 v[42:43], v156
	v_cvt_pk_f32_fp8_sdwa v[44:45], v156 src0_sel:WORD_1
	v_cvt_pk_f32_fp8_e32 v[46:47], v157
	v_cvt_pk_f32_fp8_sdwa v[48:49], v157 src0_sel:WORD_1
	v_cvt_pk_f32_fp8_e32 v[50:51], v158
	v_cvt_pk_f32_fp8_sdwa v[52:53], v158 src0_sel:WORD_1
	v_cvt_pk_f32_fp8_e32 v[54:55], v159
	v_cvt_pk_f32_fp8_sdwa v[56:57], v159 src0_sel:WORD_1
	global_load_dwordx4 v[152:155], v76, s[12:13]
	global_load_dwordx4 v[156:159], v77, s[12:13]
	v_pk_mul_f32 v[58:59], v[26:27], v[10:11]
	v_pk_mul_f32 v[60:61], v[42:43], v[10:11]
	v_pk_fma_f32 v[58:59], v[28:29], v[12:13], v[58:59]
	v_pk_fma_f32 v[60:61], v[44:45], v[12:13], v[60:61]
	v_pk_fma_f32 v[58:59], v[30:31], v[14:15], v[58:59]
	v_pk_fma_f32 v[60:61], v[46:47], v[14:15], v[60:61]
	v_pk_fma_f32 v[58:59], v[32:33], v[16:17], v[58:59]
	v_pk_fma_f32 v[60:61], v[48:49], v[16:17], v[60:61]
	v_pk_fma_f32 v[58:59], v[34:35], v[18:19], v[58:59]
	v_pk_fma_f32 v[60:61], v[50:51], v[18:19], v[60:61]
	v_pk_fma_f32 v[58:59], v[36:37], v[20:21], v[58:59]
	v_pk_fma_f32 v[60:61], v[52:53], v[20:21], v[60:61]
	v_pk_fma_f32 v[58:59], v[38:39], v[22:23], v[58:59]
	v_pk_fma_f32 v[60:61], v[54:55], v[22:23], v[60:61]
	v_pk_fma_f32 v[58:59], v[40:41], v[24:25], v[58:59]
	v_pk_fma_f32 v[60:61], v[56:57], v[24:25], v[60:61]
	v_add_f32_e32 v112, v58, v59
	v_add_f32_e32 v113, v60, v61
	s_waitcnt vmcnt(20)
; DEVI float gelu_f(float x) { const float u = 0.7978845608028654f * (x + 0.044715f * x * x * x); return x * __builtin_amdgcn_rcpf(1.f + __expf(-2.f * u)); }
;     ...
;     for (int t = 0; t < NTL; ++t) { b0[t] = *(const u32x4_t*)(up[t]); b1[t] = *(const u32x4_t*)(up[t] + 64); }
;     ...
;     for (int m = 0; m < 16; m += 2) {
;         const u32x4_t a0 = *(const u32x4_t*)(hp + m * 64), a1 = *(const u32x4_t*)(hp + m * 64 + 64);
; #pragma unroll
;         for (int t = 0; t < NTL; ++t) FP8MM(a0, b0[t], acc[t]);
;         if (m + 2 < 16) {
; #pragma unroll
;             for (int t = 0; t < NTL; ++t) b0[t] = *(const u32x4_t*)(up[t] + (m + 2) * 64);
;         }
; #pragma unroll
;         for (int t = 0; t < NTL; ++t) FP8MM(a1, b1[t], acc[t]);
;         if (m + 3 < 16) {
; #pragma unroll
;             for (int t = 0; t < NTL; ++t) b1[t] = *(const u32x4_t*)(up[t] + (m + 3) * 64);
;         }
;     }
;     ...
; #pragma unroll
;     for (int t = 0; t < NTL; ++t) { const float lo = __shfl_xor(acc[t][0], 32); const float dot = (acc[t][0] + lo * (1.f / 32.f)) * s_u[t];
;         if (kq == 0) pl[t * 16 + n16] = (u32x2_t){(unsigned)e[t], __float_as_uint(g[t] * gelu_f(dot) * s_v[t])}; }
	v_cvt_pk_f32_fp8_e32 v[26:27], v160
	v_cvt_pk_f32_fp8_sdwa v[28:29], v160 src0_sel:WORD_1
	v_cvt_pk_f32_fp8_e32 v[30:31], v161
	v_cvt_pk_f32_fp8_sdwa v[32:33], v161 src0_sel:WORD_1
	v_cvt_pk_f32_fp8_e32 v[34:35], v162
	v_cvt_pk_f32_fp8_sdwa v[36:37], v162 src0_sel:WORD_1
	v_cvt_pk_f32_fp8_e32 v[38:39], v163
	v_cvt_pk_f32_fp8_sdwa v[40:41], v163 src0_sel:WORD_1
	v_cvt_pk_f32_fp8_e32 v[42:43], v164
	v_cvt_pk_f32_fp8_sdwa v[44:45], v164 src0_sel:WORD_1
	v_cvt_pk_f32_fp8_e32 v[46:47], v165
	v_cvt_pk_f32_fp8_sdwa v[48:49], v165 src0_sel:WORD_1
	v_cvt_pk_f32_fp8_e32 v[50:51], v166
	v_cvt_pk_f32_fp8_sdwa v[52:53], v166 src0_sel:WORD_1
	v_cvt_pk_f32_fp8_e32 v[54:55], v167
	v_cvt_pk_f32_fp8_sdwa v[56:57], v167 src0_sel:WORD_1
	global_load_dwordx4 v[160:163], v78, s[12:13]
	global_load_dwordx4 v[164:167], v79, s[12:13]
	v_pk_mul_f32 v[58:59], v[26:27], v[10:11]
	v_pk_mul_f32 v[60:61], v[42:43], v[10:11]
	v_pk_fma_f32 v[58:59], v[28:29], v[12:13], v[58:59]
	v_pk_fma_f32 v[60:61], v[44:45], v[12:13], v[60:61]
	v_pk_fma_f32 v[58:59], v[30:31], v[14:15], v[58:59]
	v_pk_fma_f32 v[60:61], v[46:47], v[14:15], v[60:61]
	v_pk_fma_f32 v[58:59], v[32:33], v[16:17], v[58:59]
	v_pk_fma_f32 v[60:61], v[48:49], v[16:17], v[60:61]
	v_pk_fma_f32 v[58:59], v[34:35], v[18:19], v[58:59]
	v_pk_fma_f32 v[60:61], v[50:51], v[18:19], v[60:61]
	v_pk_fma_f32 v[58:59], v[36:37], v[20:21], v[58:59]
	v_pk_fma_f32 v[60:61], v[52:53], v[20:21], v[60:61]
	v_pk_fma_f32 v[58:59], v[38:39], v[22:23], v[58:59]
	v_pk_fma_f32 v[60:61], v[54:55], v[22:23], v[60:61]
	v_pk_fma_f32 v[58:59], v[40:41], v[24:25], v[58:59]
	v_pk_fma_f32 v[60:61], v[56:57], v[24:25], v[60:61]
	v_add_f32_e32 v114, v58, v59
	v_add_f32_e32 v115, v60, v61
	s_waitcnt vmcnt(20)
	v_cvt_pk_f32_fp8_e32 v[26:27], v168
	v_cvt_pk_f32_fp8_sdwa v[28:29], v168 src0_sel:WORD_1
	v_cvt_pk_f32_fp8_e32 v[30:31], v169
	v_cvt_pk_f32_fp8_sdwa v[32:33], v169 src0_sel:WORD_1
	v_cvt_pk_f32_fp8_e32 v[34:35], v170
	v_cvt_pk_f32_fp8_sdwa v[36:37], v170 src0_sel:WORD_1
	v_cvt_pk_f32_fp8_e32 v[38:39], v171
	v_cvt_pk_f32_fp8_sdwa v[40:41], v171 src0_sel:WORD_1
	v_cvt_pk_f32_fp8_e32 v[42:43], v172
	v_cvt_pk_f32_fp8_sdwa v[44:45], v172 src0_sel:WORD_1
	v_cvt_pk_f32_fp8_e32 v[46:47], v173
	v_cvt_pk_f32_fp8_sdwa v[48:49], v173 src0_sel:WORD_1
	v_cvt_pk_f32_fp8_e32 v[50:51], v174
	v_cvt_pk_f32_fp8_sdwa v[52:53], v174 src0_sel:WORD_1
	v_cvt_pk_f32_fp8_e32 v[54:55], v175
	v_cvt_pk_f32_fp8_sdwa v[56:57], v175 src0_sel:WORD_1
	global_load_dwordx4 v[168:171], v80, s[12:13]
	global_load_dwordx4 v[172:175], v81, s[12:13]
	v_pk_mul_f32 v[58:59], v[26:27], v[10:11]
	v_pk_mul_f32 v[60:61], v[42:43], v[10:11]
	v_pk_fma_f32 v[58:59], v[28:29], v[12:13], v[58:59]
	v_pk_fma_f32 v[60:61], v[44:45], v[12:13], v[60:61]
	v_pk_fma_f32 v[58:59], v[30:31], v[14:15], v[58:59]
	v_pk_fma_f32 v[60:61], v[46:47], v[14:15], v[60:61]
	v_pk_fma_f32 v[58:59], v[32:33], v[16:17], v[58:59]
	v_pk_fma_f32 v[60:61], v[48:49], v[16:17], v[60:61]
	v_pk_fma_f32 v[58:59], v[34:35], v[18:19], v[58:59]
	v_pk_fma_f32 v[60:61], v[50:51], v[18:19], v[60:61]
	v_pk_fma_f32 v[58:59], v[36:37], v[20:21], v[58:59]
	v_pk_fma_f32 v[60:61], v[52:53], v[20:21], v[60:61]
	v_pk_fma_f32 v[58:59], v[38:39], v[22:23], v[58:59]
	v_pk_fma_f32 v[60:61], v[54:55], v[22:23], v[60:61]
	v_pk_fma_f32 v[58:59], v[40:41], v[24:25], v[58:59]
	v_pk_fma_f32 v[60:61], v[56:57], v[24:25], v[60:61]
	v_add_f32_e32 v62, v58, v59
	v_add_f32_e32 v63, v60, v61
	s_waitcnt vmcnt(20)
	v_cvt_pk_f32_fp8_e32 v[26:27], v188
	v_cvt_pk_f32_fp8_sdwa v[28:29], v188 src0_sel:WORD_1
	v_cvt_pk_f32_fp8_e32 v[30:31], v189
	v_cvt_pk_f32_fp8_sdwa v[32:33], v189 src0_sel:WORD_1
	v_cvt_pk_f32_fp8_e32 v[34:35], v190
	v_cvt_pk_f32_fp8_sdwa v[36:37], v190 src0_sel:WORD_1
	v_cvt_pk_f32_fp8_e32 v[38:39], v191
	v_cvt_pk_f32_fp8_sdwa v[40:41], v191 src0_sel:WORD_1
	v_cvt_pk_f32_fp8_e32 v[42:43], v192
	v_cvt_pk_f32_fp8_sdwa v[44:45], v192 src0_sel:WORD_1
	v_cvt_pk_f32_fp8_e32 v[46:47], v193
	v_cvt_pk_f32_fp8_sdwa v[48:49], v193 src0_sel:WORD_1
	v_cvt_pk_f32_fp8_e32 v[50:51], v194
	v_cvt_pk_f32_fp8_sdwa v[52:53], v194 src0_sel:WORD_1
	v_cvt_pk_f32_fp8_e32 v[54:55], v195
	v_cvt_pk_f32_fp8_sdwa v[56:57], v195 src0_sel:WORD_1
	global_load_dwordx4 v[188:191], v82, s[12:13]
	global_load_dwordx4 v[192:195], v83, s[12:13]
	v_pk_mul_f32 v[58:59], v[26:27], v[10:11]
	v_pk_mul_f32 v[60:61], v[42:43], v[10:11]
	v_pk_fma_f32 v[58:59], v[28:29], v[12:13], v[58:59]
	v_pk_fma_f32 v[60:61], v[44:45], v[12:13], v[60:61]
	v_pk_fma_f32 v[58:59], v[30:31], v[14:15], v[58:59]
	v_pk_fma_f32 v[60:61], v[46:47], v[14:15], v[60:61]
	v_pk_fma_f32 v[58:59], v[32:33], v[16:17], v[58:59]
	v_pk_fma_f32 v[60:61], v[48:49], v[16:17], v[60:61]
	v_pk_fma_f32 v[58:59], v[34:35], v[18:19], v[58:59]
	v_pk_fma_f32 v[60:61], v[50:51], v[18:19], v[60:61]
	v_pk_fma_f32 v[58:59], v[36:37], v[20:21], v[58:59]
	v_pk_fma_f32 v[60:61], v[52:53], v[20:21], v[60:61]
	v_pk_fma_f32 v[58:59], v[38:39], v[22:23], v[58:59]
	v_pk_fma_f32 v[60:61], v[54:55], v[22:23], v[60:61]
	v_pk_fma_f32 v[58:59], v[40:41], v[24:25], v[58:59]
	v_pk_fma_f32 v[60:61], v[56:57], v[24:25], v[60:61]
	v_add_f32_e32 v64, v58, v59
	v_add_f32_e32 v65, v60, v61
	s_nop 1
	v_add_f32_dpp v104, v104, v104 row_half_mirror row_mask:0xf bank_mask:0x5
	v_add_f32_dpp v104, v112, v112 row_half_mirror row_mask:0xf bank_mask:0xa
	v_add_f32_dpp v105, v105, v105 row_half_mirror row_mask:0xf bank_mask:0x5
	v_add_f32_dpp v105, v113, v113 row_half_mirror row_mask:0xf bank_mask:0xa
	v_add_f32_dpp v106, v106, v106 row_half_mirror row_mask:0xf bank_mask:0x5
	v_add_f32_dpp v106, v114, v114 row_half_mirror row_mask:0xf bank_mask:0xa
;     DEVI int* eidx() const { return (int*)(ws + WS_EIDX); }
; DEVI float gelu_f(float x) { const float u = 0.7978845608028654f * (x + 0.044715f * x * x * x); return x * __builtin_amdgcn_rcpf(1.f + __expf(-2.f * u)); }
;     ...
;     int e[NTL]; float g[NTL], s_u[NTL], s_v[NTL];
; #pragma unroll
;     for (int t = 0; t < NTL; ++t) { e[t] = eidx[(size_t)r * 128 + (tbase + t) * 16 + n16]; g[t] = gwv[(size_t)r * 128 + (tbase + t) * 16 + n16]; }
; #pragma unroll
;     for (int t = 0; t < NTL; ++t) { s_u[t] = su[e[t]]; s_v[t] = sv[e[t]]; }
;     ...
;     for (int t = 0; t < NTL; ++t) { const float lo = __shfl_xor(acc[t][0], 32); const float dot = (acc[t][0] + lo * (1.f / 32.f)) * s_u[t];
;         if (kq == 0) pl[t * 16 + n16] = (u32x2_t){(unsigned)e[t], __float_as_uint(g[t] * gelu_f(dot) * s_v[t])}; }
	v_add_f32_dpp v107, v107, v107 row_half_mirror row_mask:0xf bank_mask:0x5
	v_add_f32_dpp v107, v115, v115 row_half_mirror row_mask:0xf bank_mask:0xa
	v_add_f32_dpp v108, v108, v108 row_half_mirror row_mask:0xf bank_mask:0x5
	v_add_f32_dpp v108, v62, v62 row_half_mirror row_mask:0xf bank_mask:0xa
	v_add_f32_dpp v109, v109, v109 row_half_mirror row_mask:0xf bank_mask:0x5
	v_add_f32_dpp v109, v63, v63 row_half_mirror row_mask:0xf bank_mask:0xa
	v_add_f32_dpp v110, v110, v110 row_half_mirror row_mask:0xf bank_mask:0x5
	v_add_f32_dpp v110, v64, v64 row_half_mirror row_mask:0xf bank_mask:0xa
	v_add_f32_dpp v111, v111, v111 row_half_mirror row_mask:0xf bank_mask:0x5
	v_add_f32_dpp v111, v65, v65 row_half_mirror row_mask:0xf bank_mask:0xa
	v_cndmask_b32_e64 v26, v104, v106, s[40:41]
	v_cndmask_b32_e64 v27, v106, v104, s[40:41]
	v_cndmask_b32_e64 v28, v105, v107, s[40:41]
	v_cndmask_b32_e64 v29, v107, v105, s[40:41]
	v_cndmask_b32_e64 v30, v108, v110, s[40:41]
	v_cndmask_b32_e64 v31, v110, v108, s[40:41]
	v_cndmask_b32_e64 v32, v109, v111, s[40:41]
	v_cndmask_b32_e64 v33, v111, v109, s[40:41]
	v_add_f32_dpp v104, v27, v26 quad_perm:[1,0,3,2] row_mask:0xf bank_mask:0xf
	v_add_f32_dpp v105, v29, v28 quad_perm:[1,0,3,2] row_mask:0xf bank_mask:0xf
	v_add_f32_dpp v108, v31, v30 quad_perm:[1,0,3,2] row_mask:0xf bank_mask:0xf
	v_add_f32_dpp v109, v33, v32 quad_perm:[1,0,3,2] row_mask:0xf bank_mask:0xf
	v_cndmask_b32_e64 v26, v104, v108, s[42:43]
	v_cndmask_b32_e64 v27, v108, v104, s[42:43]
	v_cndmask_b32_e64 v28, v105, v109, s[42:43]
	v_cndmask_b32_e64 v29, v109, v105, s[42:43]
	s_nop 0
	v_add_f32_dpp v118, v27, v26 quad_perm:[2,3,0,1] row_mask:0xf bank_mask:0xf
	v_add_f32_dpp v119, v29, v28 quad_perm:[2,3,0,1] row_mask:0xf bank_mask:0xf
	s_and_b32 s9, s22, 7
	s_lshl_b32 s9, s9, 10
	v_add_u32_e32 v7, s9, v6
	ds_add_f32 v7, v118 offset:4
	ds_add_f32 v7, v119 offset:12
	s_add_u32 s22, s22, 1
	s_cmp_lg_u32 s22, 64
	s_cbranch_scc1 .Lg1_loop
	s_waitcnt vmcnt(0) lgkmcnt(0)
	s_lshl_b32 s9, s48, 9
	s_lshl_b32 s20, s34, 9
	s_add_u32 s10, s6, 0x1b292100
	s_addc_u32 s11, s7, 0
	s_add_u32 s10, s10, s9
	s_addc_u32 s11, s11, 0
	s_add_u32 s12, s6, 0x1bb12100
	s_addc_u32 s13, s7, 0
	s_add_u32 s12, s12, s9
	s_addc_u32 s13, s13, 0
	s_lshl_b32 s9, s8, 16
	s_add_u32 s16, s6, 0x2fa42100
	s_addc_u32 s17, s7, 0
	s_add_u32 s16, s16, s9
	s_addc_u32 s17, s17, 0
	s_add_u32 s18, s16, 0x40000
	s_addc_u32 s19, s17, 0
	v_lshlrev_b32_e32 v2, 3, v1
	v_lshl_add_u32 v3, v1, 4, s85
	ds_read_b128 v[68:71], v3 offset:0
	ds_read_b128 v[72:75], v3 offset:1024
	ds_read_b128 v[76:79], v3 offset:2048
	ds_read_b128 v[80:83], v3 offset:3072
	ds_read_b128 v[84:87], v3 offset:4096
	ds_read_b128 v[88:91], v3 offset:5120
	ds_read_b128 v[92:95], v3 offset:6144
	ds_read_b128 v[96:99], v3 offset:7168
	global_load_dwordx2 v[20:21], v2, s[10:11]
	global_load_dwordx2 v[22:23], v2, s[12:13]
	s_add_u32 s10, s10, s20
	s_addc_u32 s11, s11, 0
	s_add_u32 s12, s12, s20
	s_addc_u32 s13, s13, 0
	global_load_dwordx2 v[24:25], v2, s[10:11]
	global_load_dwordx2 v[26:27], v2, s[12:13]
	s_add_u32 s10, s10, s20
	s_addc_u32 s11, s11, 0
	s_add_u32 s12, s12, s20
	s_addc_u32 s13, s13, 0
	global_load_dwordx2 v[28:29], v2, s[10:11]
	global_load_dwordx2 v[30:31], v2, s[12:13]
	s_add_u32 s10, s10, s20
	s_addc_u32 s11, s11, 0
	s_add_u32 s12, s12, s20
	s_addc_u32 s13, s13, 0
	global_load_dwordx2 v[32:33], v2, s[10:11]
	global_load_dwordx2 v[34:35], v2, s[12:13]
	s_add_u32 s10, s10, s20
	s_addc_u32 s11, s11, 0
	s_add_u32 s12, s12, s20
	s_addc_u32 s13, s13, 0
	global_load_dwordx2 v[36:37], v2, s[10:11]
	global_load_dwordx2 v[38:39], v2, s[12:13]
	s_add_u32 s10, s10, s20
	s_addc_u32 s11, s11, 0
	s_add_u32 s12, s12, s20
	s_addc_u32 s13, s13, 0
	global_load_dwordx2 v[40:41], v2, s[10:11]
	global_load_dwordx2 v[42:43], v2, s[12:13]
	s_add_u32 s10, s10, s20
	s_addc_u32 s11, s11, 0
	s_add_u32 s12, s12, s20
	s_addc_u32 s13, s13, 0
	global_load_dwordx2 v[44:45], v2, s[10:11]
	global_load_dwordx2 v[46:47], v2, s[12:13]
	s_add_u32 s10, s10, s20
	s_addc_u32 s11, s11, 0
	s_add_u32 s12, s12, s20
	s_addc_u32 s13, s13, 0
	global_load_dwordx2 v[48:49], v2, s[10:11]
	global_load_dwordx2 v[50:51], v2, s[12:13]
	s_add_u32 s10, s10, s20
	s_addc_u32 s11, s11, 0
	s_add_u32 s12, s12, s20
	s_addc_u32 s13, s13, 0
	s_waitcnt vmcnt(15)
	v_lshlrev_b32_e32 v4, 2, v20
	v_lshlrev_b32_e32 v5, 2, v21
	global_load_dword v120, v4, s[16:17]
	global_load_dword v121, v5, s[16:17]
	global_load_dword v122, v4, s[18:19]
	global_load_dword v123, v5, s[18:19]
	s_waitcnt vmcnt(17)
	v_lshlrev_b32_e32 v4, 2, v24
	v_lshlrev_b32_e32 v5, 2, v25
	global_load_dword v124, v4, s[16:17]
	global_load_dword v125, v5, s[16:17]
	global_load_dword v126, v4, s[18:19]
	global_load_dword v127, v5, s[18:19]
	s_waitcnt vmcnt(19)
	v_lshlrev_b32_e32 v4, 2, v28
	v_lshlrev_b32_e32 v5, 2, v29
	global_load_dword v128, v4, s[16:17]
	global_load_dword v129, v5, s[16:17]
	global_load_dword v130, v4, s[18:19]
	global_load_dword v131, v5, s[18:19]
	s_waitcnt vmcnt(21)
	v_lshlrev_b32_e32 v4, 2, v32
	v_lshlrev_b32_e32 v5, 2, v33
	global_load_dword v132, v4, s[16:17]
	global_load_dword v133, v5, s[16:17]
	global_load_dword v134, v4, s[18:19]
	global_load_dword v135, v5, s[18:19]
	s_waitcnt vmcnt(23)
	v_lshlrev_b32_e32 v4, 2, v36
	v_lshlrev_b32_e32 v5, 2, v37
	global_load_dword v136, v4, s[16:17]
	global_load_dword v137, v5, s[16:17]
	global_load_dword v138, v4, s[18:19]
	global_load_dword v139, v5, s[18:19]
	s_waitcnt vmcnt(25)
	v_lshlrev_b32_e32 v4, 2, v40
	v_lshlrev_b32_e32 v5, 2, v41
	global_load_dword v140, v4, s[16:17]
	global_load_dword v141, v5, s[16:17]
	global_load_dword v142, v4, s[18:19]
	global_load_dword v143, v5, s[18:19]
	s_waitcnt vmcnt(27)
; DEVI float gelu_f(float x) { const float u = 0.7978845608028654f * (x + 0.044715f * x * x * x); return x * __builtin_amdgcn_rcpf(1.f + __expf(-2.f * u)); }
;     ...
;     for (int t = 0; t < NTL; ++t) { const float lo = __shfl_xor(acc[t][0], 32); const float dot = (acc[t][0] + lo * (1.f / 32.f)) * s_u[t];
;         if (kq == 0) pl[t * 16 + n16] = (u32x2_t){(unsigned)e[t], __float_as_uint(g[t] * gelu_f(dot) * s_v[t])}; }
	v_lshlrev_b32_e32 v4, 2, v44
	v_lshlrev_b32_e32 v5, 2, v45
	global_load_dword v144, v4, s[16:17]
	global_load_dword v145, v5, s[16:17]
	global_load_dword v146, v4, s[18:19]
	global_load_dword v147, v5, s[18:19]
	s_waitcnt vmcnt(29)
	v_lshlrev_b32_e32 v4, 2, v48
	v_lshlrev_b32_e32 v5, 2, v49
	global_load_dword v148, v4, s[16:17]
	global_load_dword v149, v5, s[16:17]
	global_load_dword v150, v4, s[18:19]
	global_load_dword v151, v5, s[18:19]
	s_waitcnt lgkmcnt(0)
	s_waitcnt vmcnt(28)
	v_mul_f32_e32 v69, v69, v120
	v_mul_f32_e32 v6, 0x3d372713, v69
	v_mul_f32_e32 v6, v69, v6
	v_fma_f32 v6, v69, v6, v69
	v_mul_f32_e32 v6, 0x3f4c422a, v6
	v_mul_f32_e32 v6, -2.0, v6
	v_mul_f32_e32 v6, 0x3fb8aa3b, v6
	v_exp_f32_e32 v6, v6
	s_nop 0
	v_add_f32_e32 v6, 1.0, v6
	v_rcp_f32_e32 v6, v6
	s_nop 0
	v_mul_f32_e32 v69, v69, v6
	v_mul_f32_e32 v69, v22, v69
	v_mul_f32_e32 v69, v122, v69
	v_mul_f32_e32 v71, v71, v121
	v_mul_f32_e32 v7, 0x3d372713, v71
	v_mul_f32_e32 v7, v71, v7
	v_fma_f32 v7, v71, v7, v71
	v_mul_f32_e32 v7, 0x3f4c422a, v7
	v_mul_f32_e32 v7, -2.0, v7
	v_mul_f32_e32 v7, 0x3fb8aa3b, v7
	v_exp_f32_e32 v7, v7
	s_nop 0
	v_add_f32_e32 v7, 1.0, v7
	v_rcp_f32_e32 v7, v7
	s_nop 0
	v_mul_f32_e32 v71, v71, v7
	v_mul_f32_e32 v71, v23, v71
	v_mul_f32_e32 v71, v123, v71
	v_mov_b32_e32 v68, v20
	v_mov_b32_e32 v70, v21
	ds_write_b128 v3, v[68:71] offset:0
	s_waitcnt vmcnt(24)
	v_mul_f32_e32 v73, v73, v124
	v_mul_f32_e32 v6, 0x3d372713, v73
	v_mul_f32_e32 v6, v73, v6
	v_fma_f32 v6, v73, v6, v73
	v_mul_f32_e32 v6, 0x3f4c422a, v6
	v_mul_f32_e32 v6, -2.0, v6
	v_mul_f32_e32 v6, 0x3fb8aa3b, v6
	v_exp_f32_e32 v6, v6
	s_nop 0
	v_add_f32_e32 v6, 1.0, v6
	v_rcp_f32_e32 v6, v6
	s_nop 0
	v_mul_f32_e32 v73, v73, v6
	v_mul_f32_e32 v73, v26, v73
	v_mul_f32_e32 v73, v126, v73
	v_mul_f32_e32 v75, v75, v125
	v_mul_f32_e32 v7, 0x3d372713, v75
	v_mul_f32_e32 v7, v75, v7
	v_fma_f32 v7, v75, v7, v75
	v_mul_f32_e32 v7, 0x3f4c422a, v7
	v_mul_f32_e32 v7, -2.0, v7
	v_mul_f32_e32 v7, 0x3fb8aa3b, v7
	v_exp_f32_e32 v7, v7
	s_nop 0
	v_add_f32_e32 v7, 1.0, v7
	v_rcp_f32_e32 v7, v7
	s_nop 0
	v_mul_f32_e32 v75, v75, v7
	v_mul_f32_e32 v75, v27, v75
	v_mul_f32_e32 v75, v127, v75
	v_mov_b32_e32 v72, v24
	v_mov_b32_e32 v74, v25
	ds_write_b128 v3, v[72:75] offset:1024
	s_waitcnt vmcnt(20)
	v_mul_f32_e32 v77, v77, v128
	v_mul_f32_e32 v6, 0x3d372713, v77
	v_mul_f32_e32 v6, v77, v6
	v_fma_f32 v6, v77, v6, v77
	v_mul_f32_e32 v6, 0x3f4c422a, v6
	v_mul_f32_e32 v6, -2.0, v6
	v_mul_f32_e32 v6, 0x3fb8aa3b, v6
	v_exp_f32_e32 v6, v6
	s_nop 0
	v_add_f32_e32 v6, 1.0, v6
	v_rcp_f32_e32 v6, v6
	s_nop 0
	v_mul_f32_e32 v77, v77, v6
	v_mul_f32_e32 v77, v30, v77
	v_mul_f32_e32 v77, v130, v77
	v_mul_f32_e32 v79, v79, v129
	v_mul_f32_e32 v7, 0x3d372713, v79
	v_mul_f32_e32 v7, v79, v7
	v_fma_f32 v7, v79, v7, v79
	v_mul_f32_e32 v7, 0x3f4c422a, v7
	v_mul_f32_e32 v7, -2.0, v7
	v_mul_f32_e32 v7, 0x3fb8aa3b, v7
	v_exp_f32_e32 v7, v7
	s_nop 0
	v_add_f32_e32 v7, 1.0, v7
	v_rcp_f32_e32 v7, v7
	s_nop 0
	v_mul_f32_e32 v79, v79, v7
	v_mul_f32_e32 v79, v31, v79
	v_mul_f32_e32 v79, v131, v79
	v_mov_b32_e32 v76, v28
	v_mov_b32_e32 v78, v29
	ds_write_b128 v3, v[76:79] offset:2048
	s_waitcnt vmcnt(16)
	v_mul_f32_e32 v81, v81, v132
	v_mul_f32_e32 v6, 0x3d372713, v81
	v_mul_f32_e32 v6, v81, v6
	v_fma_f32 v6, v81, v6, v81
	v_mul_f32_e32 v6, 0x3f4c422a, v6
	v_mul_f32_e32 v6, -2.0, v6
	v_mul_f32_e32 v6, 0x3fb8aa3b, v6
	v_exp_f32_e32 v6, v6
	s_nop 0
	v_add_f32_e32 v6, 1.0, v6
	v_rcp_f32_e32 v6, v6
	s_nop 0
	v_mul_f32_e32 v81, v81, v6
	v_mul_f32_e32 v81, v34, v81
	v_mul_f32_e32 v81, v134, v81
	v_mul_f32_e32 v83, v83, v133
	v_mul_f32_e32 v7, 0x3d372713, v83
	v_mul_f32_e32 v7, v83, v7
	v_fma_f32 v7, v83, v7, v83
	v_mul_f32_e32 v7, 0x3f4c422a, v7
	v_mul_f32_e32 v7, -2.0, v7
	v_mul_f32_e32 v7, 0x3fb8aa3b, v7
	v_exp_f32_e32 v7, v7
	s_nop 0
	v_add_f32_e32 v7, 1.0, v7
	v_rcp_f32_e32 v7, v7
	s_nop 0
	v_mul_f32_e32 v83, v83, v7
	v_mul_f32_e32 v83, v35, v83
	v_mul_f32_e32 v83, v135, v83
	v_mov_b32_e32 v80, v32
	v_mov_b32_e32 v82, v33
	ds_write_b128 v3, v[80:83] offset:3072
	s_waitcnt vmcnt(12)
	v_mul_f32_e32 v85, v85, v136
	v_mul_f32_e32 v6, 0x3d372713, v85
	v_mul_f32_e32 v6, v85, v6
	v_fma_f32 v6, v85, v6, v85
	v_mul_f32_e32 v6, 0x3f4c422a, v6
	v_mul_f32_e32 v6, -2.0, v6
	v_mul_f32_e32 v6, 0x3fb8aa3b, v6
	v_exp_f32_e32 v6, v6
	s_nop 0
	v_add_f32_e32 v6, 1.0, v6
	v_rcp_f32_e32 v6, v6
	s_nop 0
	v_mul_f32_e32 v85, v85, v6
	v_mul_f32_e32 v85, v38, v85
	v_mul_f32_e32 v85, v138, v85
	v_mul_f32_e32 v87, v87, v137
	v_mul_f32_e32 v7, 0x3d372713, v87
	v_mul_f32_e32 v7, v87, v7
	v_fma_f32 v7, v87, v7, v87
	v_mul_f32_e32 v7, 0x3f4c422a, v7
	v_mul_f32_e32 v7, -2.0, v7
	v_mul_f32_e32 v7, 0x3fb8aa3b, v7
	v_exp_f32_e32 v7, v7
	s_nop 0
	v_add_f32_e32 v7, 1.0, v7
	v_rcp_f32_e32 v7, v7
	s_nop 0
	v_mul_f32_e32 v87, v87, v7
	v_mul_f32_e32 v87, v39, v87
	v_mul_f32_e32 v87, v139, v87
	v_mov_b32_e32 v84, v36
	v_mov_b32_e32 v86, v37
	ds_write_b128 v3, v[84:87] offset:4096
	s_waitcnt vmcnt(8)
	v_mul_f32_e32 v89, v89, v140
	v_mul_f32_e32 v6, 0x3d372713, v89
	v_mul_f32_e32 v6, v89, v6
	v_fma_f32 v6, v89, v6, v89
	v_mul_f32_e32 v6, 0x3f4c422a, v6
	v_mul_f32_e32 v6, -2.0, v6
	v_mul_f32_e32 v6, 0x3fb8aa3b, v6
	v_exp_f32_e32 v6, v6
	s_nop 0
	v_add_f32_e32 v6, 1.0, v6
	v_rcp_f32_e32 v6, v6
	s_nop 0
	v_mul_f32_e32 v89, v89, v6
	v_mul_f32_e32 v89, v42, v89
	v_mul_f32_e32 v89, v142, v89
	v_mul_f32_e32 v91, v91, v141
	v_mul_f32_e32 v7, 0x3d372713, v91
	v_mul_f32_e32 v7, v91, v7
	v_fma_f32 v7, v91, v7, v91
	v_mul_f32_e32 v7, 0x3f4c422a, v7
	v_mul_f32_e32 v7, -2.0, v7
	v_mul_f32_e32 v7, 0x3fb8aa3b, v7
	v_exp_f32_e32 v7, v7
	s_nop 0
	v_add_f32_e32 v7, 1.0, v7
	v_rcp_f32_e32 v7, v7
	s_nop 0
	v_mul_f32_e32 v91, v91, v7
	v_mul_f32_e32 v91, v43, v91
	v_mul_f32_e32 v91, v143, v91
	v_mov_b32_e32 v88, v40
	v_mov_b32_e32 v90, v41
	ds_write_b128 v3, v[88:91] offset:5120
	s_waitcnt vmcnt(4)
;     ...
;     for (int j0 = 0; j0 < NTL * 16; j0 += 16) {
;         u32x4_t w[16]; float cj[16];
; #pragma unroll
;         for (int jj = 0; jj < 16; ++jj) { const u32x2_t pr = pl[j0 + jj]; const int ej = __builtin_amdgcn_readfirstlane((int)pr.x); cj[jj] = __uint_as_float(pr.y);
;             w[jj] = *(const u32x4_t*)(v8 + (size_t)ej * D + 16 * lane); }
	v_mul_f32_e32 v93, v93, v144
	v_mul_f32_e32 v6, 0x3d372713, v93
	v_mul_f32_e32 v6, v93, v6
	v_fma_f32 v6, v93, v6, v93
	v_mul_f32_e32 v6, 0x3f4c422a, v6
	v_mul_f32_e32 v6, -2.0, v6
	v_mul_f32_e32 v6, 0x3fb8aa3b, v6
	v_exp_f32_e32 v6, v6
	s_nop 0
	v_add_f32_e32 v6, 1.0, v6
	v_rcp_f32_e32 v6, v6
	s_nop 0
	v_mul_f32_e32 v93, v93, v6
	v_mul_f32_e32 v93, v46, v93
	v_mul_f32_e32 v93, v146, v93
	v_mul_f32_e32 v95, v95, v145
	v_mul_f32_e32 v7, 0x3d372713, v95
	v_mul_f32_e32 v7, v95, v7
	v_fma_f32 v7, v95, v7, v95
	v_mul_f32_e32 v7, 0x3f4c422a, v7
	v_mul_f32_e32 v7, -2.0, v7
	v_mul_f32_e32 v7, 0x3fb8aa3b, v7
	v_exp_f32_e32 v7, v7
	s_nop 0
	v_add_f32_e32 v7, 1.0, v7
	v_rcp_f32_e32 v7, v7
	s_nop 0
	v_mul_f32_e32 v95, v95, v7
	v_mul_f32_e32 v95, v47, v95
	v_mul_f32_e32 v95, v147, v95
	v_mov_b32_e32 v92, v44
	v_mov_b32_e32 v94, v45
	ds_write_b128 v3, v[92:95] offset:6144
	s_waitcnt vmcnt(0)
	v_mul_f32_e32 v97, v97, v148
	v_mul_f32_e32 v6, 0x3d372713, v97
	v_mul_f32_e32 v6, v97, v6
	v_fma_f32 v6, v97, v6, v97
	v_mul_f32_e32 v6, 0x3f4c422a, v6
	v_mul_f32_e32 v6, -2.0, v6
	v_mul_f32_e32 v6, 0x3fb8aa3b, v6
	v_exp_f32_e32 v6, v6
	s_nop 0
	v_add_f32_e32 v6, 1.0, v6
	v_rcp_f32_e32 v6, v6
	s_nop 0
	v_mul_f32_e32 v97, v97, v6
	v_mul_f32_e32 v97, v50, v97
	v_mul_f32_e32 v97, v150, v97
	v_mul_f32_e32 v99, v99, v149
	v_mul_f32_e32 v7, 0x3d372713, v99
	v_mul_f32_e32 v7, v99, v7
	v_fma_f32 v7, v99, v7, v99
	v_mul_f32_e32 v7, 0x3f4c422a, v7
	v_mul_f32_e32 v7, -2.0, v7
	v_mul_f32_e32 v7, 0x3fb8aa3b, v7
	v_exp_f32_e32 v7, v7
	s_nop 0
	v_add_f32_e32 v7, 1.0, v7
	v_rcp_f32_e32 v7, v7
	s_nop 0
	v_mul_f32_e32 v99, v99, v7
	v_mul_f32_e32 v99, v51, v99
	v_mul_f32_e32 v99, v151, v99
	v_mov_b32_e32 v96, v48
	v_mov_b32_e32 v98, v49
	ds_write_b128 v3, v[96:99] offset:7168
	s_waitcnt lgkmcnt(0)
	v_cmp_gt_u32_e32 vcc, 8, v116
	s_nop 1
	s_lshl_b32 s20, s34, 12
	s_lshl_b32 s11, s8, 24
	s_add_u32 s56, s6, 0x27a42100
	s_addc_u32 s57, s7, 0
	s_add_u32 s56, s56, s11
	s_addc_u32 s57, s57, 0
	s_mov_b32 s12, s56
	s_mov_b32 s13, s57
	s_lshl_b32 s11, s48, 12
	s_add_u32 s58, s4, s11
	s_addc_u32 s59, s5, 0
	s_mul_i32 s11, s8, 0x6c000
	s_add_u32 s60, s6, 0x9000
	s_addc_u32 s61, s7, 0
	s_add_u32 s60, s60, s11
	s_addc_u32 s61, s61, 0
	s_mov_b32 s24, 0xff00ff00
	s_mov_b32 s25, 0xff00ff00
	v_and_b32_e32 v2, 7, v1
	v_lshrrev_b32_e32 v3, 3, v1
	v_lshlrev_b32_e32 v4, 4, v2
	v_lshlrev_b32_e32 v5, 7, v3
	v_add_u32_e32 v5, s85, v5
	v_lshlrev_b32_e32 v6, 6, v2
	v_lshl_add_u32 v6, v3, 3, v6
	ds_read_b128 v[26:29], v5 offset:0
	ds_read_b128 v[30:33], v5 offset:16
	ds_read_b128 v[34:37], v5 offset:32
	ds_read_b128 v[38:41], v5 offset:48
	ds_read_b128 v[42:45], v5 offset:64
	ds_read_b128 v[46:49], v5 offset:80
	ds_read_b128 v[50:53], v5 offset:96
	ds_read_b128 v[54:57], v5 offset:112
	s_waitcnt lgkmcnt(0)
	v_lshl_add_u32 v68, v26, 10, v4
	v_lshl_add_u32 v69, v28, 10, v4
	v_lshl_add_u32 v70, v30, 10, v4
	v_lshl_add_u32 v71, v32, 10, v4
	v_lshl_add_u32 v72, v34, 10, v4
	v_lshl_add_u32 v73, v36, 10, v4
	v_lshl_add_u32 v74, v38, 10, v4
	v_lshl_add_u32 v75, v40, 10, v4
	v_lshl_add_u32 v76, v42, 10, v4
	v_lshl_add_u32 v77, v44, 10, v4
	v_lshl_add_u32 v78, v46, 10, v4
	v_lshl_add_u32 v79, v48, 10, v4
	v_lshl_add_u32 v80, v50, 10, v4
	v_lshl_add_u32 v81, v52, 10, v4
	v_lshl_add_u32 v82, v54, 10, v4
	v_lshl_add_u32 v83, v56, 10, v4
	global_load_dwordx4 v[120:123], v68, s[12:13]
	global_load_dwordx4 v[124:127], v69, s[12:13]
	global_load_dwordx4 v[128:131], v70, s[12:13]
	global_load_dwordx4 v[132:135], v71, s[12:13]
	global_load_dwordx4 v[136:139], v72, s[12:13]
	global_load_dwordx4 v[140:143], v73, s[12:13]
	global_load_dwordx4 v[144:147], v74, s[12:13]
	global_load_dwordx4 v[148:151], v75, s[12:13]
	global_load_dwordx4 v[152:155], v76, s[12:13]
	global_load_dwordx4 v[156:159], v77, s[12:13]
	global_load_dwordx4 v[160:163], v78, s[12:13]
	global_load_dwordx4 v[164:167], v79, s[12:13]
	global_load_dwordx4 v[168:171], v80, s[12:13]
	global_load_dwordx4 v[172:175], v81, s[12:13]
	global_load_dwordx4 v[188:191], v82, s[12:13]
	global_load_dwordx4 v[192:195], v83, s[12:13]
	s_mov_b32 s22, 0
	s_add_u32 s9, s22, 0
	s_and_b32 s9, s9, 7
	s_lshl_b32 s9, s9, 10
	v_add_u32_e32 v7, s9, v5
	s_add_u32 s9, s22, 1
	s_and_b32 s9, s9, 7
	s_lshl_b32 s9, s9, 10
	v_add_u32_e32 v8, s9, v5
	ds_read_b128 v[84:87], v7 offset:0
	ds_read_b128 v[88:91], v7 offset:16
	ds_read_b128 v[92:95], v7 offset:32
	ds_read_b128 v[96:99], v7 offset:48
	ds_read_b128 v[104:107], v7 offset:64
	ds_read_b128 v[108:111], v7 offset:80
	ds_read_b128 v[112:115], v7 offset:96
	ds_read_b128 v[180:183], v7 offset:112
	ds_read_b128 v[26:29], v8 offset:0
	ds_read_b128 v[30:33], v8 offset:16
	ds_read_b128 v[34:37], v8 offset:32
	ds_read_b128 v[38:41], v8 offset:48
	ds_read_b128 v[42:45], v8 offset:64
	ds_read_b128 v[46:49], v8 offset:80
	ds_read_b128 v[50:53], v8 offset:96
	ds_read_b128 v[54:57], v8 offset:112
	s_waitcnt lgkmcnt(0)
	v_lshl_add_u32 v68, v26, 10, v4
	v_lshl_add_u32 v69, v28, 10, v4
	v_lshl_add_u32 v70, v30, 10, v4
	v_lshl_add_u32 v71, v32, 10, v4
	v_lshl_add_u32 v72, v34, 10, v4
	v_lshl_add_u32 v73, v36, 10, v4
	v_lshl_add_u32 v74, v38, 10, v4
	v_lshl_add_u32 v75, v40, 10, v4
	v_lshl_add_u32 v76, v42, 10, v4
	v_lshl_add_u32 v77, v44, 10, v4
	v_lshl_add_u32 v78, v46, 10, v4
	v_lshl_add_u32 v79, v48, 10, v4
	v_lshl_add_u32 v80, v50, 10, v4
	v_lshl_add_u32 v81, v52, 10, v4
	v_lshl_add_u32 v82, v54, 10, v4
	v_lshl_add_u32 v83, v56, 10, v4

;     ...
;     for (int j0 = 0; j0 < NTL * 16; j0 += 16) {
;         u32x4_t w[16]; float cj[16];
; #pragma unroll
;         for (int jj = 0; jj < 16; ++jj) { const u32x2_t pr = pl[j0 + jj]; const int ej = __builtin_amdgcn_readfirstlane((int)pr.x); cj[jj] = __uint_as_float(pr.y);
;             w[jj] = *(const u32x4_t*)(v8 + (size_t)ej * D + 16 * lane); }
; #pragma unroll
;         for (int jj = 0; jj < 16; ++jj) { const float c = cj[jj];
; #pragma unroll
;             for (int q = 0; q < 4; ++q) { const f32x2_t lo = __builtin_amdgcn_cvt_pk_f32_fp8((int)w[jj][q], false), hi = __builtin_amdgcn_cvt_pk_f32_fp8((int)w[jj][q], true);
;                 o[4 * q] += c * lo[0]; o[4 * q + 1] += c * lo[1]; o[4 * q + 2] += c * hi[0]; o[4 * q + 3] += c * hi[1]; } }
.Lg2_nobar:
	s_and_b32 s9, s22, 7
	s_lshr_b32 s10, s22, 3
	s_mul_i32 s11, s9, s20
	s_lshl_b32 s23, s10, 9
	s_add_u32 s14, s58, s11
	s_addc_u32 s15, s59, 0
	s_add_u32 s14, s14, s23
	s_addc_u32 s15, s15, 0
	s_mul_i32 s11, s9, s34
	s_add_u32 s11, s11, s48
	s_lshr_b32 s11, s11, 13
	s_mul_i32 s11, s11, 0x6000
	s_add_u32 s16, s60, s11
	s_addc_u32 s17, s61, 0
	s_add_u32 s16, s16, s23
	s_addc_u32 s17, s17, 0
	global_load_dwordx2 v[58:59], v6, s[14:15]
	global_load_dwordx2 v[60:61], v6, s[16:17]
	s_add_u32 s10, s22, 1
	s_lshr_b32 s10, s10, 3
	s_lshl_b32 s10, s10, 7
	s_add_u32 s12, s56, s10
	s_addc_u32 s13, s57, 0
	s_waitcnt vmcnt(16)
	v_cvt_pk_f32_fp8_e32 v[26:27], v120
	v_cvt_pk_f32_fp8_sdwa v[28:29], v120 src0_sel:WORD_1
	v_cvt_pk_f32_fp8_e32 v[30:31], v121
	v_cvt_pk_f32_fp8_sdwa v[32:33], v121 src0_sel:WORD_1
	v_cvt_pk_f32_fp8_e32 v[34:35], v122
	v_cvt_pk_f32_fp8_sdwa v[36:37], v122 src0_sel:WORD_1
	v_cvt_pk_f32_fp8_e32 v[38:39], v123
	v_cvt_pk_f32_fp8_sdwa v[40:41], v123 src0_sel:WORD_1
	v_cvt_pk_f32_fp8_e32 v[42:43], v124
	v_cvt_pk_f32_fp8_sdwa v[44:45], v124 src0_sel:WORD_1
	v_cvt_pk_f32_fp8_e32 v[46:47], v125
	v_cvt_pk_f32_fp8_sdwa v[48:49], v125 src0_sel:WORD_1
	v_cvt_pk_f32_fp8_e32 v[50:51], v126
	v_cvt_pk_f32_fp8_sdwa v[52:53], v126 src0_sel:WORD_1
	v_cvt_pk_f32_fp8_e32 v[54:55], v127
	v_cvt_pk_f32_fp8_sdwa v[56:57], v127 src0_sel:WORD_1
	global_load_dwordx4 v[120:123], v68, s[12:13]
	global_load_dwordx4 v[124:127], v69, s[12:13]
	v_pk_mul_f32 v[10:11], v[84:85], v[26:27] op_sel:[1,0]
	v_pk_mul_f32 v[12:13], v[84:85], v[28:29] op_sel:[1,0]
	v_pk_mul_f32 v[14:15], v[84:85], v[30:31] op_sel:[1,0]
	v_pk_mul_f32 v[16:17], v[84:85], v[32:33] op_sel:[1,0]
	v_pk_mul_f32 v[18:19], v[84:85], v[34:35] op_sel:[1,0]
	v_pk_mul_f32 v[20:21], v[84:85], v[36:37] op_sel:[1,0]
	v_pk_mul_f32 v[22:23], v[84:85], v[38:39] op_sel:[1,0]
	v_pk_mul_f32 v[24:25], v[84:85], v[40:41] op_sel:[1,0]
	v_pk_fma_f32 v[10:11], v[86:87], v[42:43], v[10:11] op_sel:[1,0,0]
	v_pk_fma_f32 v[12:13], v[86:87], v[44:45], v[12:13] op_sel:[1,0,0]
	v_pk_fma_f32 v[14:15], v[86:87], v[46:47], v[14:15] op_sel:[1,0,0]
	v_pk_fma_f32 v[16:17], v[86:87], v[48:49], v[16:17] op_sel:[1,0,0]
	v_pk_fma_f32 v[18:19], v[86:87], v[50:51], v[18:19] op_sel:[1,0,0]
	v_pk_fma_f32 v[20:21], v[86:87], v[52:53], v[20:21] op_sel:[1,0,0]
	v_pk_fma_f32 v[22:23], v[86:87], v[54:55], v[22:23] op_sel:[1,0,0]
	v_pk_fma_f32 v[24:25], v[86:87], v[56:57], v[24:25] op_sel:[1,0,0]
	s_waitcnt vmcnt(16)
	v_cvt_pk_f32_fp8_e32 v[26:27], v128
	v_cvt_pk_f32_fp8_sdwa v[28:29], v128 src0_sel:WORD_1
	v_cvt_pk_f32_fp8_e32 v[30:31], v129
	v_cvt_pk_f32_fp8_sdwa v[32:33], v129 src0_sel:WORD_1
	v_cvt_pk_f32_fp8_e32 v[34:35], v130
	v_cvt_pk_f32_fp8_sdwa v[36:37], v130 src0_sel:WORD_1
	v_cvt_pk_f32_fp8_e32 v[38:39], v131
	v_cvt_pk_f32_fp8_sdwa v[40:41], v131 src0_sel:WORD_1
	v_cvt_pk_f32_fp8_e32 v[42:43], v132
	v_cvt_pk_f32_fp8_sdwa v[44:45], v132 src0_sel:WORD_1
	v_cvt_pk_f32_fp8_e32 v[46:47], v133
	v_cvt_pk_f32_fp8_sdwa v[48:49], v133 src0_sel:WORD_1
	v_cvt_pk_f32_fp8_e32 v[50:51], v134
	v_cvt_pk_f32_fp8_sdwa v[52:53], v134 src0_sel:WORD_1
	v_cvt_pk_f32_fp8_e32 v[54:55], v135
	v_cvt_pk_f32_fp8_sdwa v[56:57], v135 src0_sel:WORD_1
	global_load_dwordx4 v[128:131], v70, s[12:13]
	global_load_dwordx4 v[132:135], v71, s[12:13]
	v_pk_fma_f32 v[10:11], v[88:89], v[26:27], v[10:11] op_sel:[1,0,0]
	v_pk_fma_f32 v[12:13], v[88:89], v[28:29], v[12:13] op_sel:[1,0,0]
	v_pk_fma_f32 v[14:15], v[88:89], v[30:31], v[14:15] op_sel:[1,0,0]
	v_pk_fma_f32 v[16:17], v[88:89], v[32:33], v[16:17] op_sel:[1,0,0]
	v_pk_fma_f32 v[18:19], v[88:89], v[34:35], v[18:19] op_sel:[1,0,0]
	v_pk_fma_f32 v[20:21], v[88:89], v[36:37], v[20:21] op_sel:[1,0,0]
	v_pk_fma_f32 v[22:23], v[88:89], v[38:39], v[22:23] op_sel:[1,0,0]
	v_pk_fma_f32 v[24:25], v[88:89], v[40:41], v[24:25] op_sel:[1,0,0]
	v_pk_fma_f32 v[10:11], v[90:91], v[42:43], v[10:11] op_sel:[1,0,0]
	v_pk_fma_f32 v[12:13], v[90:91], v[44:45], v[12:13] op_sel:[1,0,0]
	v_pk_fma_f32 v[14:15], v[90:91], v[46:47], v[14:15] op_sel:[1,0,0]
	v_pk_fma_f32 v[16:17], v[90:91], v[48:49], v[16:17] op_sel:[1,0,0]
	v_pk_fma_f32 v[18:19], v[90:91], v[50:51], v[18:19] op_sel:[1,0,0]
	v_pk_fma_f32 v[20:21], v[90:91], v[52:53], v[20:21] op_sel:[1,0,0]
	v_pk_fma_f32 v[22:23], v[90:91], v[54:55], v[22:23] op_sel:[1,0,0]
	v_pk_fma_f32 v[24:25], v[90:91], v[56:57], v[24:25] op_sel:[1,0,0]
	s_waitcnt vmcnt(16)
	v_cvt_pk_f32_fp8_e32 v[26:27], v136
	v_cvt_pk_f32_fp8_sdwa v[28:29], v136 src0_sel:WORD_1
	v_cvt_pk_f32_fp8_e32 v[30:31], v137
	v_cvt_pk_f32_fp8_sdwa v[32:33], v137 src0_sel:WORD_1
	v_cvt_pk_f32_fp8_e32 v[34:35], v138
	v_cvt_pk_f32_fp8_sdwa v[36:37], v138 src0_sel:WORD_1
	v_cvt_pk_f32_fp8_e32 v[38:39], v139
	v_cvt_pk_f32_fp8_sdwa v[40:41], v139 src0_sel:WORD_1
	v_cvt_pk_f32_fp8_e32 v[42:43], v140
	v_cvt_pk_f32_fp8_sdwa v[44:45], v140 src0_sel:WORD_1
	v_cvt_pk_f32_fp8_e32 v[46:47], v141
	v_cvt_pk_f32_fp8_sdwa v[48:49], v141 src0_sel:WORD_1
	v_cvt_pk_f32_fp8_e32 v[50:51], v142
	v_cvt_pk_f32_fp8_sdwa v[52:53], v142 src0_sel:WORD_1
	v_cvt_pk_f32_fp8_e32 v[54:55], v143
	v_cvt_pk_f32_fp8_sdwa v[56:57], v143 src0_sel:WORD_1
	global_load_dwordx4 v[136:139], v72, s[12:13]
	global_load_dwordx4 v[140:143], v73, s[12:13]
	v_pk_fma_f32 v[10:11], v[92:93], v[26:27], v[10:11] op_sel:[1,0,0]
	v_pk_fma_f32 v[12:13], v[92:93], v[28:29], v[12:13] op_sel:[1,0,0]
	v_pk_fma_f32 v[14:15], v[92:93], v[30:31], v[14:15] op_sel:[1,0,0]
	v_pk_fma_f32 v[16:17], v[92:93], v[32:33], v[16:17] op_sel:[1,0,0]
	v_pk_fma_f32 v[18:19], v[92:93], v[34:35], v[18:19] op_sel:[1,0,0]
	v_pk_fma_f32 v[20:21], v[92:93], v[36:37], v[20:21] op_sel:[1,0,0]
	v_pk_fma_f32 v[22:23], v[92:93], v[38:39], v[22:23] op_sel:[1,0,0]
	v_pk_fma_f32 v[24:25], v[92:93], v[40:41], v[24:25] op_sel:[1,0,0]
	v_pk_fma_f32 v[10:11], v[94:95], v[42:43], v[10:11] op_sel:[1,0,0]
	v_pk_fma_f32 v[12:13], v[94:95], v[44:45], v[12:13] op_sel:[1,0,0]
	v_pk_fma_f32 v[14:15], v[94:95], v[46:47], v[14:15] op_sel:[1,0,0]
	v_pk_fma_f32 v[16:17], v[94:95], v[48:49], v[16:17] op_sel:[1,0,0]
	v_pk_fma_f32 v[18:19], v[94:95], v[50:51], v[18:19] op_sel:[1,0,0]
	v_pk_fma_f32 v[20:21], v[94:95], v[52:53], v[20:21] op_sel:[1,0,0]
	v_pk_fma_f32 v[22:23], v[94:95], v[54:55], v[22:23] op_sel:[1,0,0]
	v_pk_fma_f32 v[24:25], v[94:95], v[56:57], v[24:25] op_sel:[1,0,0]
	s_waitcnt vmcnt(16)
;     ...
;     for (int j0 = 0; j0 < NTL * 16; j0 += 16) {
;         u32x4_t w[16]; float cj[16];
; #pragma unroll
;         for (int jj = 0; jj < 16; ++jj) { const u32x2_t pr = pl[j0 + jj]; const int ej = __builtin_amdgcn_readfirstlane((int)pr.x); cj[jj] = __uint_as_float(pr.y);
;             w[jj] = *(const u32x4_t*)(v8 + (size_t)ej * D + 16 * lane); }
; #pragma unroll
;         for (int jj = 0; jj < 16; ++jj) { const float c = cj[jj];
; #pragma unroll
;             for (int q = 0; q < 4; ++q) { const f32x2_t lo = __builtin_amdgcn_cvt_pk_f32_fp8((int)w[jj][q], false), hi = __builtin_amdgcn_cvt_pk_f32_fp8((int)w[jj][q], true);
;                 o[4 * q] += c * lo[0]; o[4 * q + 1] += c * lo[1]; o[4 * q + 2] += c * hi[0]; o[4 * q + 3] += c * hi[1]; } }
	v_cvt_pk_f32_fp8_e32 v[26:27], v144
	v_cvt_pk_f32_fp8_sdwa v[28:29], v144 src0_sel:WORD_1
	v_cvt_pk_f32_fp8_e32 v[30:31], v145
	v_cvt_pk_f32_fp8_sdwa v[32:33], v145 src0_sel:WORD_1
	v_cvt_pk_f32_fp8_e32 v[34:35], v146
	v_cvt_pk_f32_fp8_sdwa v[36:37], v146 src0_sel:WORD_1
	v_cvt_pk_f32_fp8_e32 v[38:39], v147
	v_cvt_pk_f32_fp8_sdwa v[40:41], v147 src0_sel:WORD_1
	v_cvt_pk_f32_fp8_e32 v[42:43], v148
	v_cvt_pk_f32_fp8_sdwa v[44:45], v148 src0_sel:WORD_1
	v_cvt_pk_f32_fp8_e32 v[46:47], v149
	v_cvt_pk_f32_fp8_sdwa v[48:49], v149 src0_sel:WORD_1
	v_cvt_pk_f32_fp8_e32 v[50:51], v150
	v_cvt_pk_f32_fp8_sdwa v[52:53], v150 src0_sel:WORD_1
	v_cvt_pk_f32_fp8_e32 v[54:55], v151
	v_cvt_pk_f32_fp8_sdwa v[56:57], v151 src0_sel:WORD_1
	global_load_dwordx4 v[144:147], v74, s[12:13]
	global_load_dwordx4 v[148:151], v75, s[12:13]
	v_pk_fma_f32 v[10:11], v[96:97], v[26:27], v[10:11] op_sel:[1,0,0]
	v_pk_fma_f32 v[12:13], v[96:97], v[28:29], v[12:13] op_sel:[1,0,0]
	v_pk_fma_f32 v[14:15], v[96:97], v[30:31], v[14:15] op_sel:[1,0,0]
	v_pk_fma_f32 v[16:17], v[96:97], v[32:33], v[16:17] op_sel:[1,0,0]
	v_pk_fma_f32 v[18:19], v[96:97], v[34:35], v[18:19] op_sel:[1,0,0]
	v_pk_fma_f32 v[20:21], v[96:97], v[36:37], v[20:21] op_sel:[1,0,0]
	v_pk_fma_f32 v[22:23], v[96:97], v[38:39], v[22:23] op_sel:[1,0,0]
	v_pk_fma_f32 v[24:25], v[96:97], v[40:41], v[24:25] op_sel:[1,0,0]
	v_pk_fma_f32 v[10:11], v[98:99], v[42:43], v[10:11] op_sel:[1,0,0]
	v_pk_fma_f32 v[12:13], v[98:99], v[44:45], v[12:13] op_sel:[1,0,0]
	v_pk_fma_f32 v[14:15], v[98:99], v[46:47], v[14:15] op_sel:[1,0,0]
	v_pk_fma_f32 v[16:17], v[98:99], v[48:49], v[16:17] op_sel:[1,0,0]
	v_pk_fma_f32 v[18:19], v[98:99], v[50:51], v[18:19] op_sel:[1,0,0]
	v_pk_fma_f32 v[20:21], v[98:99], v[52:53], v[20:21] op_sel:[1,0,0]
	v_pk_fma_f32 v[22:23], v[98:99], v[54:55], v[22:23] op_sel:[1,0,0]
	v_pk_fma_f32 v[24:25], v[98:99], v[56:57], v[24:25] op_sel:[1,0,0]
	s_waitcnt vmcnt(16)
	v_cvt_pk_f32_fp8_e32 v[26:27], v152
	v_cvt_pk_f32_fp8_sdwa v[28:29], v152 src0_sel:WORD_1
	v_cvt_pk_f32_fp8_e32 v[30:31], v153
	v_cvt_pk_f32_fp8_sdwa v[32:33], v153 src0_sel:WORD_1
	v_cvt_pk_f32_fp8_e32 v[34:35], v154
	v_cvt_pk_f32_fp8_sdwa v[36:37], v154 src0_sel:WORD_1
	v_cvt_pk_f32_fp8_e32 v[38:39], v155
	v_cvt_pk_f32_fp8_sdwa v[40:41], v155 src0_sel:WORD_1
	v_cvt_pk_f32_fp8_e32 v[42:43], v156
	v_cvt_pk_f32_fp8_sdwa v[44:45], v156 src0_sel:WORD_1
	v_cvt_pk_f32_fp8_e32 v[46:47], v157
	v_cvt_pk_f32_fp8_sdwa v[48:49], v157 src0_sel:WORD_1
	v_cvt_pk_f32_fp8_e32 v[50:51], v158
	v_cvt_pk_f32_fp8_sdwa v[52:53], v158 src0_sel:WORD_1
	v_cvt_pk_f32_fp8_e32 v[54:55], v159
	v_cvt_pk_f32_fp8_sdwa v[56:57], v159 src0_sel:WORD_1
	global_load_dwordx4 v[152:155], v76, s[12:13]
	global_load_dwordx4 v[156:159], v77, s[12:13]
	v_pk_fma_f32 v[10:11], v[104:105], v[26:27], v[10:11] op_sel:[1,0,0]
	v_pk_fma_f32 v[12:13], v[104:105], v[28:29], v[12:13] op_sel:[1,0,0]
	v_pk_fma_f32 v[14:15], v[104:105], v[30:31], v[14:15] op_sel:[1,0,0]
	v_pk_fma_f32 v[16:17], v[104:105], v[32:33], v[16:17] op_sel:[1,0,0]
	v_pk_fma_f32 v[18:19], v[104:105], v[34:35], v[18:19] op_sel:[1,0,0]
	v_pk_fma_f32 v[20:21], v[104:105], v[36:37], v[20:21] op_sel:[1,0,0]
	v_pk_fma_f32 v[22:23], v[104:105], v[38:39], v[22:23] op_sel:[1,0,0]
	v_pk_fma_f32 v[24:25], v[104:105], v[40:41], v[24:25] op_sel:[1,0,0]
	v_pk_fma_f32 v[10:11], v[106:107], v[42:43], v[10:11] op_sel:[1,0,0]
	v_pk_fma_f32 v[12:13], v[106:107], v[44:45], v[12:13] op_sel:[1,0,0]
	v_pk_fma_f32 v[14:15], v[106:107], v[46:47], v[14:15] op_sel:[1,0,0]
	v_pk_fma_f32 v[16:17], v[106:107], v[48:49], v[16:17] op_sel:[1,0,0]
	v_pk_fma_f32 v[18:19], v[106:107], v[50:51], v[18:19] op_sel:[1,0,0]
	v_pk_fma_f32 v[20:21], v[106:107], v[52:53], v[20:21] op_sel:[1,0,0]
	v_pk_fma_f32 v[22:23], v[106:107], v[54:55], v[22:23] op_sel:[1,0,0]
	v_pk_fma_f32 v[24:25], v[106:107], v[56:57], v[24:25] op_sel:[1,0,0]
	s_waitcnt vmcnt(16)
	v_cvt_pk_f32_fp8_e32 v[26:27], v160
	v_cvt_pk_f32_fp8_sdwa v[28:29], v160 src0_sel:WORD_1
	v_cvt_pk_f32_fp8_e32 v[30:31], v161
	v_cvt_pk_f32_fp8_sdwa v[32:33], v161 src0_sel:WORD_1
	v_cvt_pk_f32_fp8_e32 v[34:35], v162
	v_cvt_pk_f32_fp8_sdwa v[36:37], v162 src0_sel:WORD_1
	v_cvt_pk_f32_fp8_e32 v[38:39], v163
	v_cvt_pk_f32_fp8_sdwa v[40:41], v163 src0_sel:WORD_1
	v_cvt_pk_f32_fp8_e32 v[42:43], v164
	v_cvt_pk_f32_fp8_sdwa v[44:45], v164 src0_sel:WORD_1
	v_cvt_pk_f32_fp8_e32 v[46:47], v165
	v_cvt_pk_f32_fp8_sdwa v[48:49], v165 src0_sel:WORD_1
	v_cvt_pk_f32_fp8_e32 v[50:51], v166
	v_cvt_pk_f32_fp8_sdwa v[52:53], v166 src0_sel:WORD_1
	v_cvt_pk_f32_fp8_e32 v[54:55], v167
	v_cvt_pk_f32_fp8_sdwa v[56:57], v167 src0_sel:WORD_1
	global_load_dwordx4 v[160:163], v78, s[12:13]
	global_load_dwordx4 v[164:167], v79, s[12:13]
	v_pk_fma_f32 v[10:11], v[108:109], v[26:27], v[10:11] op_sel:[1,0,0]
	v_pk_fma_f32 v[12:13], v[108:109], v[28:29], v[12:13] op_sel:[1,0,0]
	v_pk_fma_f32 v[14:15], v[108:109], v[30:31], v[14:15] op_sel:[1,0,0]
	v_pk_fma_f32 v[16:17], v[108:109], v[32:33], v[16:17] op_sel:[1,0,0]
	v_pk_fma_f32 v[18:19], v[108:109], v[34:35], v[18:19] op_sel:[1,0,0]
	v_pk_fma_f32 v[20:21], v[108:109], v[36:37], v[20:21] op_sel:[1,0,0]
	v_pk_fma_f32 v[22:23], v[108:109], v[38:39], v[22:23] op_sel:[1,0,0]
	v_pk_fma_f32 v[24:25], v[108:109], v[40:41], v[24:25] op_sel:[1,0,0]
	v_pk_fma_f32 v[10:11], v[110:111], v[42:43], v[10:11] op_sel:[1,0,0]
	v_pk_fma_f32 v[12:13], v[110:111], v[44:45], v[12:13] op_sel:[1,0,0]
	v_pk_fma_f32 v[14:15], v[110:111], v[46:47], v[14:15] op_sel:[1,0,0]
	v_pk_fma_f32 v[16:17], v[110:111], v[48:49], v[16:17] op_sel:[1,0,0]
	v_pk_fma_f32 v[18:19], v[110:111], v[50:51], v[18:19] op_sel:[1,0,0]
	v_pk_fma_f32 v[20:21], v[110:111], v[52:53], v[20:21] op_sel:[1,0,0]
	v_pk_fma_f32 v[22:23], v[110:111], v[54:55], v[22:23] op_sel:[1,0,0]
	v_pk_fma_f32 v[24:25], v[110:111], v[56:57], v[24:25] op_sel:[1,0,0]
	s_waitcnt vmcnt(16)
;     ...
;         for (int jj = 0; jj < 16; ++jj) { const u32x2_t pr = pl[j0 + jj]; const int ej = __builtin_amdgcn_readfirstlane((int)pr.x); cj[jj] = __uint_as_float(pr.y);
;             w[jj] = *(const u32x4_t*)(v8 + (size_t)ej * D + 16 * lane); }
; #pragma unroll
;         for (int jj = 0; jj < 16; ++jj) { const float c = cj[jj];
; #pragma unroll
;             for (int q = 0; q < 4; ++q) { const f32x2_t lo = __builtin_amdgcn_cvt_pk_f32_fp8((int)w[jj][q], false), hi = __builtin_amdgcn_cvt_pk_f32_fp8((int)w[jj][q], true);
;                 o[4 * q] += c * lo[0]; o[4 * q + 1] += c * lo[1]; o[4 * q + 2] += c * hi[0]; o[4 * q + 3] += c * hi[1]; } }
;     ...
;     const float* gp = gate2 + (size_t)row_seq(r) * 6144 + 16 * lane;
;     float* xp = x + (size_t)r * D + 16 * lane;
; #pragma unroll
;     for (int q = 0; q < 4; ++q) {
;         float4 xa = *(const float4*)(xp + 4 * q); const float4 ga = *(const float4*)(gp + 4 * q);
;         xa.x += ga.x * o[4 * q]; xa.y += ga.y * o[4 * q + 1]; xa.z += ga.z * o[4 * q + 2]; xa.w += ga.w * o[4 * q + 3];
;         *(float4*)(xp + 4 * q) = xa;
;         o[4 * q] = xa.x; o[4 * q + 1] = xa.y; o[4 * q + 2] = xa.z; o[4 * q + 3] = xa.w;
	v_cvt_pk_f32_fp8_e32 v[26:27], v168
	v_cvt_pk_f32_fp8_sdwa v[28:29], v168 src0_sel:WORD_1
	v_cvt_pk_f32_fp8_e32 v[30:31], v169
	v_cvt_pk_f32_fp8_sdwa v[32:33], v169 src0_sel:WORD_1
	v_cvt_pk_f32_fp8_e32 v[34:35], v170
	v_cvt_pk_f32_fp8_sdwa v[36:37], v170 src0_sel:WORD_1
	v_cvt_pk_f32_fp8_e32 v[38:39], v171
	v_cvt_pk_f32_fp8_sdwa v[40:41], v171 src0_sel:WORD_1
	v_cvt_pk_f32_fp8_e32 v[42:43], v172
	v_cvt_pk_f32_fp8_sdwa v[44:45], v172 src0_sel:WORD_1
	v_cvt_pk_f32_fp8_e32 v[46:47], v173
	v_cvt_pk_f32_fp8_sdwa v[48:49], v173 src0_sel:WORD_1
	v_cvt_pk_f32_fp8_e32 v[50:51], v174
	v_cvt_pk_f32_fp8_sdwa v[52:53], v174 src0_sel:WORD_1
	v_cvt_pk_f32_fp8_e32 v[54:55], v175
	v_cvt_pk_f32_fp8_sdwa v[56:57], v175 src0_sel:WORD_1
	global_load_dwordx4 v[168:171], v80, s[12:13]
	global_load_dwordx4 v[172:175], v81, s[12:13]
	v_pk_fma_f32 v[10:11], v[112:113], v[26:27], v[10:11] op_sel:[1,0,0]
	v_pk_fma_f32 v[12:13], v[112:113], v[28:29], v[12:13] op_sel:[1,0,0]
	v_pk_fma_f32 v[14:15], v[112:113], v[30:31], v[14:15] op_sel:[1,0,0]
	v_pk_fma_f32 v[16:17], v[112:113], v[32:33], v[16:17] op_sel:[1,0,0]
	v_pk_fma_f32 v[18:19], v[112:113], v[34:35], v[18:19] op_sel:[1,0,0]
	v_pk_fma_f32 v[20:21], v[112:113], v[36:37], v[20:21] op_sel:[1,0,0]
	v_pk_fma_f32 v[22:23], v[112:113], v[38:39], v[22:23] op_sel:[1,0,0]
	v_pk_fma_f32 v[24:25], v[112:113], v[40:41], v[24:25] op_sel:[1,0,0]
	v_pk_fma_f32 v[10:11], v[114:115], v[42:43], v[10:11] op_sel:[1,0,0]
	v_pk_fma_f32 v[12:13], v[114:115], v[44:45], v[12:13] op_sel:[1,0,0]
	v_pk_fma_f32 v[14:15], v[114:115], v[46:47], v[14:15] op_sel:[1,0,0]
	v_pk_fma_f32 v[16:17], v[114:115], v[48:49], v[16:17] op_sel:[1,0,0]
	v_pk_fma_f32 v[18:19], v[114:115], v[50:51], v[18:19] op_sel:[1,0,0]
	v_pk_fma_f32 v[20:21], v[114:115], v[52:53], v[20:21] op_sel:[1,0,0]
	v_pk_fma_f32 v[22:23], v[114:115], v[54:55], v[22:23] op_sel:[1,0,0]
	v_pk_fma_f32 v[24:25], v[114:115], v[56:57], v[24:25] op_sel:[1,0,0]
	s_waitcnt vmcnt(16)
	v_cvt_pk_f32_fp8_e32 v[26:27], v188
	v_cvt_pk_f32_fp8_sdwa v[28:29], v188 src0_sel:WORD_1
	v_cvt_pk_f32_fp8_e32 v[30:31], v189
	v_cvt_pk_f32_fp8_sdwa v[32:33], v189 src0_sel:WORD_1
	v_cvt_pk_f32_fp8_e32 v[34:35], v190
	v_cvt_pk_f32_fp8_sdwa v[36:37], v190 src0_sel:WORD_1
	v_cvt_pk_f32_fp8_e32 v[38:39], v191
	v_cvt_pk_f32_fp8_sdwa v[40:41], v191 src0_sel:WORD_1
	v_cvt_pk_f32_fp8_e32 v[42:43], v192
	v_cvt_pk_f32_fp8_sdwa v[44:45], v192 src0_sel:WORD_1
	v_cvt_pk_f32_fp8_e32 v[46:47], v193
	v_cvt_pk_f32_fp8_sdwa v[48:49], v193 src0_sel:WORD_1
	v_cvt_pk_f32_fp8_e32 v[50:51], v194
	v_cvt_pk_f32_fp8_sdwa v[52:53], v194 src0_sel:WORD_1
	v_cvt_pk_f32_fp8_e32 v[54:55], v195
	v_cvt_pk_f32_fp8_sdwa v[56:57], v195 src0_sel:WORD_1
	global_load_dwordx4 v[188:191], v82, s[12:13]
	global_load_dwordx4 v[192:195], v83, s[12:13]
	v_pk_fma_f32 v[10:11], v[180:181], v[26:27], v[10:11] op_sel:[1,0,0]
	v_pk_fma_f32 v[12:13], v[180:181], v[28:29], v[12:13] op_sel:[1,0,0]
	v_pk_fma_f32 v[14:15], v[180:181], v[30:31], v[14:15] op_sel:[1,0,0]
	v_pk_fma_f32 v[16:17], v[180:181], v[32:33], v[16:17] op_sel:[1,0,0]
	v_pk_fma_f32 v[18:19], v[180:181], v[34:35], v[18:19] op_sel:[1,0,0]
	v_pk_fma_f32 v[20:21], v[180:181], v[36:37], v[20:21] op_sel:[1,0,0]
	v_pk_fma_f32 v[22:23], v[180:181], v[38:39], v[22:23] op_sel:[1,0,0]
	v_pk_fma_f32 v[24:25], v[180:181], v[40:41], v[24:25] op_sel:[1,0,0]
	v_pk_fma_f32 v[10:11], v[182:183], v[42:43], v[10:11] op_sel:[1,0,0]
	v_pk_fma_f32 v[12:13], v[182:183], v[44:45], v[12:13] op_sel:[1,0,0]
	v_pk_fma_f32 v[14:15], v[182:183], v[46:47], v[14:15] op_sel:[1,0,0]
	v_pk_fma_f32 v[16:17], v[182:183], v[48:49], v[16:17] op_sel:[1,0,0]
	v_pk_fma_f32 v[18:19], v[182:183], v[50:51], v[18:19] op_sel:[1,0,0]
	v_pk_fma_f32 v[20:21], v[182:183], v[52:53], v[20:21] op_sel:[1,0,0]
	v_pk_fma_f32 v[22:23], v[182:183], v[54:55], v[22:23] op_sel:[1,0,0]
	v_pk_fma_f32 v[24:25], v[182:183], v[56:57], v[24:25] op_sel:[1,0,0]
	s_add_u32 s9, s22, 1
	s_and_b32 s9, s9, 7
	s_lshl_b32 s9, s9, 10
	v_add_u32_e32 v7, s9, v5
	s_add_u32 s9, s22, 2
	s_and_b32 s9, s9, 7
	s_lshl_b32 s9, s9, 10
	v_add_u32_e32 v8, s9, v5
	ds_read_b128 v[84:87], v7 offset:0
	ds_read_b128 v[88:91], v7 offset:16
	ds_read_b128 v[92:95], v7 offset:32
	ds_read_b128 v[96:99], v7 offset:48
	ds_read_b128 v[104:107], v7 offset:64
	ds_read_b128 v[108:111], v7 offset:80
	ds_read_b128 v[112:115], v7 offset:96
	ds_read_b128 v[180:183], v7 offset:112
	ds_read_b128 v[26:29], v8 offset:0
	ds_read_b128 v[30:33], v8 offset:16
	ds_read_b128 v[34:37], v8 offset:32
	ds_read_b128 v[38:41], v8 offset:48
	ds_read_b128 v[42:45], v8 offset:64
	ds_read_b128 v[46:49], v8 offset:80
	ds_read_b128 v[50:53], v8 offset:96
	ds_read_b128 v[54:57], v8 offset:112
	s_nop 1
	v_permlane32_swap_b32_e32 v10, v18
	v_permlane32_swap_b32_e32 v11, v19
	v_permlane32_swap_b32_e32 v12, v20
	v_permlane32_swap_b32_e32 v13, v21
	v_permlane32_swap_b32_e32 v14, v22
	v_permlane32_swap_b32_e32 v15, v23
	v_permlane32_swap_b32_e32 v16, v24
	v_permlane32_swap_b32_e32 v17, v25
	v_add_f32_e32 v10, v10, v18
	v_add_f32_e32 v11, v11, v19
	v_add_f32_e32 v12, v12, v20
	v_add_f32_e32 v13, v13, v21
	v_add_f32_e32 v14, v14, v22
	v_add_f32_e32 v15, v15, v23
	v_add_f32_e32 v16, v16, v24
	v_add_f32_e32 v17, v17, v25
	s_nop 1
	v_permlane16_swap_b32_e32 v10, v14
	v_permlane16_swap_b32_e32 v11, v15
	v_permlane16_swap_b32_e32 v12, v16
	v_permlane16_swap_b32_e32 v13, v17
	v_add_f32_e32 v10, v10, v14
	v_add_f32_e32 v11, v11, v15
	v_add_f32_e32 v12, v12, v16
	v_add_f32_e32 v13, v13, v17
	v_cndmask_b32_e64 v14, v10, v12, s[24:25]
	v_cndmask_b32_e64 v16, v12, v10, s[24:25]
	v_cndmask_b32_e64 v15, v11, v13, s[24:25]
	v_cndmask_b32_e64 v17, v13, v11, s[24:25]
	s_nop 1
	v_add_f32_dpp v62, v16, v14 row_ror:8 row_mask:0xf bank_mask:0xf
	v_add_f32_dpp v63, v17, v15 row_ror:8 row_mask:0xf bank_mask:0xf
	s_waitcnt lgkmcnt(0)
	v_lshl_add_u32 v68, v26, 10, v4
	v_lshl_add_u32 v69, v28, 10, v4
	v_lshl_add_u32 v70, v30, 10, v4
	v_lshl_add_u32 v71, v32, 10, v4
	v_lshl_add_u32 v72, v34, 10, v4
	v_lshl_add_u32 v73, v36, 10, v4
	v_lshl_add_u32 v74, v38, 10, v4
	v_lshl_add_u32 v75, v40, 10, v4
	v_lshl_add_u32 v76, v42, 10, v4
	v_lshl_add_u32 v77, v44, 10, v4
	v_lshl_add_u32 v78, v46, 10, v4
	v_lshl_add_u32 v79, v48, 10, v4
	v_lshl_add_u32 v80, v50, 10, v4
	v_lshl_add_u32 v81, v52, 10, v4
	v_lshl_add_u32 v82, v54, 10, v4
	v_lshl_add_u32 v83, v56, 10, v4
	s_waitcnt vmcnt(16)
	v_pk_fma_f32 v[58:59], v[62:63], v[60:61], v[58:59]
	global_store_dwordx2 v6, v[58:59], s[14:15]
	s_add_u32 s22, s22, 1
	s_cmp_lg_u32 s22, 64
	s_cbranch_scc1 .Lg2_loop
; DEVI void adaln_apply_1(const P& p, int l, int r, int lane, float (&v)[16]) { adaln_apply<1>(p, l, r, lane, v); }
;     ...
;     const float* gp = gate2 + (size_t)row_seq(r) * 6144 + 16 * lane;
;     float* xp = x + (size_t)r * D + 16 * lane;
; #pragma unroll
;     for (int q = 0; q < 4; ++q) {
;         float4 xa = *(const float4*)(xp + 4 * q); const float4 ga = *(const float4*)(gp + 4 * q);
;         xa.x += ga.x * o[4 * q]; xa.y += ga.y * o[4 * q + 1]; xa.z += ga.z * o[4 * q + 2]; xa.w += ga.w * o[4 * q + 3];
;         *(float4*)(xp + 4 * q) = xa;
;         o[4 * q] = xa.x; o[4 * q + 1] = xa.y; o[4 * q + 2] = xa.z; o[4 * q + 3] = xa.w;
;     }
;     __builtin_amdgcn_sched_barrier(0);
;     if (l + 1 < DEPTH) adaln_apply_1(p, l + 1, r, lane, o);
	s_waitcnt vmcnt(0)
	v_cmp_gt_u32_e32 vcc, 8, v116
	s_nop 1
	s_waitcnt vmcnt(0)
	s_barrier
	s_ashr_i32 s9, s8, 31
	s_lshl_b64 s[18:19], s[8:9], 24
	s_lshl_b64 s[10:11], s[8:9], 16
	s_add_u32 s9, s6, s10
	s_addc_u32 s13, s7, s11
	s_add_u32 s10, s9, 0x2fa42100
	s_addc_u32 s11, s13, 0
	s_add_u32 s12, s9, 0x2fa82100
	s_addc_u32 s13, s13, 0
	s_add_u32 s14, s6, 0x1b292100
	s_addc_u32 s15, s7, 0
	s_add_u32 s16, s6, 0x1bb12100
	s_addc_u32 s17, s7, 0
	s_add_u32 s18, s6, s18
	s_addc_u32 s19, s7, s19
	v_lshl_add_u64 v[2:3], s[18:19], 0, v[102:103]
	s_mov_b64 s[20:21], 0x1fa42100
	v_lshl_add_u64 v[104:105], v[2:3], 0, s[20:21]
	v_mov_b32_e32 v2, 0x1100000
	v_cndmask_b32_e64 v66, v2, 0, vcc
	v_lshl_add_u64 v[2:3], s[6:7], 0, v[66:67]
	s_add_u32 s49, s6, 0x4000
	v_lshl_add_u64 v[2:3], v[2:3], 0, v[102:103]
	s_mov_b64 s[20:21], 0x2fac2100
	s_addc_u32 s50, s7, 0
	v_lshl_add_u64 v[106:107], v[2:3], 0, s[20:21]
	s_add_u32 s20, s49, s47
	v_lshl_add_u64 v[2:3], s[18:19], 0, v[100:101]
	s_mov_b64 s[18:19], 0x27a42100
	s_addc_u32 s21, s50, s46
	v_lshl_add_u64 v[108:109], v[2:3], 0, s[18:19]
	v_lshlrev_b64 v[2:3], 2, v[100:101]
	v_lshl_add_u64 v[4:5], s[20:21], 0, v[2:3]
	s_mov_b64 s[18:19], 0x5000
	s_cmp_lt_i32 s8, 3
	v_lshl_add_u64 v[110:111], v[4:5], 0, s[18:19]
	s_cselect_b64 s[18:19], -1, 0
	s_add_i32 s24, s8, 1
	s_ashr_i32 s25, s24, 31
	s_lshl_b64 s[20:21], s[24:25], 12
	s_add_u32 s55, s6, 0x20e100
	s_addc_u32 s56, s7, 0
	s_lshl_b32 s26, s24, 2
	s_ashr_i32 s27, s26, 31
	s_mul_i32 s23, s24, 0xc000
	s_mul_hi_i32 s22, s24, 0xc000
	s_add_u32 s23, s6, s23
	s_addc_u32 s28, s7, s22
	s_add_u32 s22, s23, 0x1f812100
	s_addc_u32 s23, s28, 0
	s_add_u32 s57, s6, 0xcb8a100
	s_addc_u32 s58, s7, 0
	s_lshl_b64 s[28:29], s[24:25], 18
	s_add_u32 s59, s4, s28
	s_addc_u32 s60, s5, s29
	s_lshl_b32 s28, s24, 3
	s_ashr_i32 s29, s28, 31
	s_add_u32 s61, s6, 0xacda100
	s_mov_b32 s9, 0
	v_lshl_add_u64 v[112:113], s[4:5], 0, v[2:3]
	s_mul_hi_i32 s51, s24, 18
	s_mul_i32 s54, s24, 18
	s_addc_u32 s62, s7, 0
	s_lshl_b64 s[24:25], s[26:27], 2
	s_lshl_b64 s[26:27], s[28:29], 2
	s_mov_b32 s63, s48
	s_branch .LBB0_1087

;     DEVI float* mod() const { return (float*)(ws + WS_MOD); }
;     DEVI float* rstd() const { return (float*)(ws + WS_RSTD); }
; DEVI cfp_t inp(int i) { const __attribute__((address_space(4))) cfp_t* k = (const __attribute__((address_space(4))) cfp_t*)__builtin_amdgcn_kernarg_segment_ptr(); typedef const __attribute__((address_space(1))) float* gcfp_t; const gcfp_t r = *(const volatile __attribute__((address_space(4))) gcfp_t*)(k + i); return (cfp_t)r; }
; template <int WHICH> DEVI void adaln_apply(const P& p, int l, int r, int lane_in, float (&v)[16]) {
;     int lane = lane_in; asm volatile("" : "+v"(lane));
;     const float* g = inp(WHICH == 1 ? 9 : 10) + (size_t)l * D + 16 * lane;
;     const int osh = (WHICH == 1 ? 0 : 3) * D, osc = (WHICH == 1 ? 1 : 4) * D;
;     float ss = 0.f;
; #pragma unroll
;     for (int i = 0; i < 16; ++i) ss += v[i] * v[i];
;     const float rstd = rsqrtf(wave_sum(ss) * (1.f / D) + EPS);
;     const float* md = p.mod() + ((size_t)l * NSEQ + row_seq(r)) * 6144 + 16 * lane;
; #pragma unroll
;     for (int q = 0; q < 4; ++q) {
;         const float4 gg = *(const float4*)(g + 4 * q), sc = *(const float4*)(md + osc + 4 * q), sh = *(const float4*)(md + osh + 4 * q);
;         v[4 * q] = v[4 * q] * rstd * gg.x * (1.f + sc.x) + sh.x; v[4 * q + 1] = v[4 * q + 1] * rstd * gg.y * (1.f + sc.y) + sh.y;
;         v[4 * q + 2] = v[4 * q + 2] * rstd * gg.z * (1.f + sc.z) + sh.z; v[4 * q + 3] = v[4 * q + 3] * rstd * gg.w * (1.f + sc.w) + sh.w;
.LBB0_1111:
	s_add_i32 s28, s64, s9
	s_mul_i32 s28, s28, s34
	s_add_i32 s28, s28, s48
	s_cmpk_gt_i32 s28, 0x3fff
	s_cbranch_scc1 .LBB0_1110
	v_mov_b32_e32 v114, 0
	s_mov_b32 s29, -16
	s_mov_b32 s30, s65
	v_mov_b32_e32 v115, v114
	v_mov_b32_e32 v120, v114
	v_mov_b32_e32 v121, v114
	v_mov_b32_e32 v118, v114
	v_mov_b32_e32 v119, v114
	v_mov_b32_e32 v128, v114
	v_mov_b32_e32 v129, v114
	v_mov_b32_e32 v130, v114
	v_mov_b32_e32 v131, v114
	v_mov_b32_e32 v122, v114
	v_mov_b32_e32 v123, v114
	v_mov_b32_e32 v124, v114
	v_mov_b32_e32 v125, v114
	v_mov_b32_e32 v126, v114
	v_mov_b32_e32 v127, v114
	s_ashr_i32 s29, s28, 31
	s_lshr_b32 s30, s29, 19
	s_add_i32 s30, s28, s30
	s_ashr_i32 s30, s30, 13
	s_lshl_b64 s[40:41], s[28:29], 12
	s_nop 0
	v_lshl_add_u64 v[16:17], v[112:113], 0, s[40:41]
	global_load_dwordx4 v[30:33], v[16:17], off sc1
	global_load_dwordx4 v[22:25], v[16:17], off offset:16 sc1
	global_load_dwordx4 v[26:29], v[16:17], off offset:32 sc1
	global_load_dwordx4 v[18:21], v[16:17], off offset:48 sc1
	s_waitcnt vmcnt(0)
	s_and_b64 vcc, exec, s[18:19]
	s_cbranch_vccz .LBB0_1110
	v_pk_mul_f32 v[2:3], v[30:31], v[30:31]
	v_pk_mul_f32 v[4:5], v[32:33], v[32:33]
	v_add_f32_e32 v2, v2, v3
	v_add_f32_e32 v2, v4, v2
	v_pk_mul_f32 v[6:7], v[22:23], v[22:23]
	v_add_f32_e32 v2, v5, v2
	v_add_f32_e32 v2, v2, v6
	v_pk_mul_f32 v[8:9], v[24:25], v[24:25]
	v_add_f32_e32 v2, v7, v2
	v_add_f32_e32 v2, v8, v2
	v_pk_mul_f32 v[10:11], v[26:27], v[26:27]
	v_add_f32_e32 v2, v9, v2
	v_add_f32_e32 v2, v2, v10
	v_pk_mul_f32 v[12:13], v[28:29], v[28:29]
	v_add_f32_e32 v2, v11, v2
	v_add_f32_e32 v2, v12, v2
	v_pk_mul_f32 v[14:15], v[18:19], v[18:19]
	v_add_f32_e32 v2, v13, v2
	v_add_f32_e32 v2, v2, v14
	v_pk_mul_f32 v[16:17], v[20:21], v[20:21]
	v_add_f32_e32 v2, v15, v2
	v_add_f32_e32 v2, v16, v2
	v_add_f32_e32 v4, v17, v2
	ds_bpermute_b32 v5, v179, v4
	v_mov_b32_e32 v58, v1
	s_load_dwordx2 s[40:41], s[0:1], 0x48
	s_ashr_i32 s31, s30, 31
	s_waitcnt lgkmcnt(0)
	v_add_f32_e32 v4, v4, v5
	ds_bpermute_b32 v5, v204, v4
	v_lshlrev_b32_e32 v60, 4, v58
	v_ashrrev_i32_e32 v61, 31, v60
	s_add_u32 s40, s40, s20
	s_addc_u32 s41, s41, s21
	s_waitcnt lgkmcnt(0)
	v_add_f32_e32 v4, v4, v5
	ds_bpermute_b32 v5, v205, v4
	v_lshlrev_b64 v[62:63], 2, v[60:61]
	v_lshl_add_u64 v[2:3], s[40:41], 0, v[62:63]
	s_mov_b32 s40, 0x800000
	s_add_u32 s30, s54, s30
	s_waitcnt lgkmcnt(0)
	v_add_f32_e32 v4, v4, v5
	ds_bpermute_b32 v5, v206, v4
	s_addc_u32 s31, s51, s31
	s_mulk_i32 s31, 0x6000
	s_mov_b64 s[42:43], 0x1000
	global_load_dwordx4 v[34:37], v[2:3], off offset:48
	global_load_dwordx4 v[38:41], v[2:3], off offset:32
	global_load_dwordx4 v[50:53], v[2:3], off offset:16
	global_load_dwordx4 v[68:71], v[2:3], off
	s_waitcnt lgkmcnt(0)
	v_add_f32_e32 v4, v4, v5
	ds_bpermute_b32 v5, v207, v4
	s_waitcnt lgkmcnt(0)
	v_add_f32_e32 v4, v4, v5
	ds_bpermute_b32 v5, v208, v4
	s_waitcnt lgkmcnt(0)
	v_add_f32_e32 v4, v4, v5
	v_fmamk_f32 v4, v4, 0x3a800000, v211
	v_cmp_gt_f32_e32 vcc, s40, v4
	v_mul_f32_e32 v5, 0x4b800000, v4
	s_mul_hi_u32 s40, s30, 0x6000
	v_cndmask_b32_e32 v4, v4, v5, vcc
	v_rsq_f32_e32 v4, v4
	s_add_i32 s40, s40, s31
	s_mulk_i32 s30, 0x6000
	s_add_u32 s30, s49, s30
	s_addc_u32 s31, s50, s40
	v_mul_f32_e32 v5, 0x45800000, v4
	v_lshl_add_u64 v[14:15], s[30:31], 0, v[62:63]
	s_movk_i32 s30, 0x1000
	v_cndmask_b32_e32 v59, v4, v5, vcc
	v_add_co_u32_e32 v2, vcc, s30, v14
	v_lshl_add_u64 v[4:5], v[14:15], 0, s[42:43]
	s_nop 0
	v_addc_co_u32_e32 v3, vcc, 0, v15, vcc
	global_load_dwordx4 v[72:75], v[2:3], off
	global_load_dwordx4 v[42:45], v[4:5], off offset:48
	global_load_dwordx4 v[46:49], v[4:5], off offset:32
	global_load_dwordx4 v[54:57], v[4:5], off offset:16
	s_nop 0
	global_load_dwordx4 v[2:5], v[14:15], off offset:48
	global_load_dwordx4 v[6:9], v[14:15], off offset:32
	global_load_dwordx4 v[10:13], v[14:15], off offset:16
	s_nop 0
	global_load_dwordx4 v[14:17], v[14:15], off
	v_mul_f32_e32 v30, v30, v59
	v_mul_f32_e32 v22, v22, v59
	s_lshl_b64 s[30:31], s[28:29], 11
	s_add_u32 s30, s55, s30
	s_addc_u32 s31, s56, s31
	s_waitcnt vmcnt(9)
	v_mul_f32_e32 v22, v22, v50
	s_waitcnt vmcnt(8)
	v_mul_f32_e32 v30, v68, v30
	s_waitcnt vmcnt(7)
	v_add_f32_e32 v64, 1.0, v72
	s_waitcnt vmcnt(0)
	v_fma_f32 v14, v64, v30, v14
	v_mul_f32_e32 v30, v31, v59
	v_mul_f32_e32 v30, v69, v30
	v_add_f32_e32 v31, 1.0, v73
	v_fma_f32 v15, v31, v30, v15
	v_mul_f32_e32 v30, v32, v59
	v_mul_f32_e32 v30, v70, v30
	v_add_f32_e32 v31, 1.0, v74
	v_fma_f32 v16, v31, v30, v16
	v_mul_f32_e32 v30, v33, v59
	v_mul_f32_e32 v30, v71, v30
	v_add_f32_e32 v31, 1.0, v75
	v_fmac_f32_e32 v17, v31, v30
	v_add_f32_e32 v30, 1.0, v54
	v_fma_f32 v50, v22, v30, v10
	v_mul_f32_e32 v10, v23, v59
	v_mul_f32_e32 v10, v10, v51
	v_add_f32_e32 v22, 1.0, v55
	v_fma_f32 v51, v10, v22, v11
	v_mul_f32_e32 v10, v24, v59
	v_mul_f32_e32 v10, v10, v52
	v_add_f32_e32 v11, 1.0, v56
	v_fma_f32 v12, v10, v11, v12
	v_mul_f32_e32 v10, v25, v59
	v_mul_f32_e32 v10, v10, v53
	v_add_f32_e32 v11, 1.0, v57
	v_fmac_f32_e32 v13, v10, v11
	v_mul_f32_e32 v10, v26, v59
	v_mul_f32_e32 v10, v10, v38
	v_add_f32_e32 v11, 1.0, v46
	v_fma_f32 v38, v10, v11, v6
	v_mul_f32_e32 v6, v27, v59
	v_mul_f32_e32 v6, v6, v39
	v_add_f32_e32 v10, 1.0, v47
	v_fma_f32 v39, v6, v10, v7
	v_mul_f32_e32 v6, v28, v59
	v_mul_f32_e32 v6, v6, v40
	v_add_f32_e32 v7, 1.0, v48
	v_fma_f32 v40, v6, v7, v8
	v_mul_f32_e32 v6, v29, v59
	v_mul_f32_e32 v6, v6, v41
	v_add_f32_e32 v7, 1.0, v49
	v_fmac_f32_e32 v9, v6, v7
	v_mul_f32_e32 v6, v18, v59
	v_mul_f32_e32 v6, v6, v34
	v_add_f32_e32 v7, 1.0, v42
	v_fma_f32 v34, v6, v7, v2
	v_mul_f32_e32 v2, v19, v59
	v_mul_f32_e32 v2, v2, v35
	v_add_f32_e32 v6, 1.0, v43
;     DEVI bf16_t* hb() const { return (bf16_t*)(ws + WS_HB); }
;     DEVI float* wsmall() const { return (float*)(ws + WS_WSMALL); }
; DEVI cfp_t inp(int i) { const __attribute__((address_space(4))) cfp_t* k = (const __attribute__((address_space(4))) cfp_t*)__builtin_amdgcn_kernarg_segment_ptr(); typedef const __attribute__((address_space(1))) float* gcfp_t; const gcfp_t r = *(const volatile __attribute__((address_space(4))) gcfp_t*)(k + i); return (cfp_t)r; }
; DEVI unsigned pk2bf(float lo, float hi) { unsigned r; asm volatile("v_cvt_pk_bf16_f32 %0, %1, %2" : "=v"(r) : "v"(lo), "v"(hi)); return r; }
; template <int WHICH> DEVI void adaln_apply(const P& p, int l, int r, int lane_in, float (&v)[16]) {
;     ...
;     u32x4_t* ob = (u32x4_t*)(p.hb() + (size_t)r * D + 16 * lane);
;     ob[0] = (u32x4_t){pk2bf(v[0], v[1]), pk2bf(v[2], v[3]), pk2bf(v[4], v[5]), pk2bf(v[6], v[7])};
;     ob[1] = (u32x4_t){pk2bf(v[8], v[9]), pk2bf(v[10], v[11]), pk2bf(v[12], v[13]), pk2bf(v[14], v[15])};
;     if constexpr (WHICH == 2) {
;         unsigned hi8[4], lo8[4];
; #pragma unroll
;         for (int q = 0; q < 4; ++q) { hi8[q] = pk4fp8(v[4 * q], v[4 * q + 1], v[4 * q + 2], v[4 * q + 3]);
;             const f32x2_t h01 = __builtin_amdgcn_cvt_pk_f32_fp8((int)hi8[q], false), h23 = __builtin_amdgcn_cvt_pk_f32_fp8((int)hi8[q], true);
;             lo8[q] = pk4fp8((v[4 * q] - h01[0]) * 32.f, (v[4 * q + 1] - h01[1]) * 32.f, (v[4 * q + 2] - h23[0]) * 32.f, (v[4 * q + 3] - h23[1]) * 32.f); }
;         *(u32x4_t*)(p.h8() + (size_t)r * D + 16 * lane) = (u32x4_t){hi8[0], hi8[1], hi8[2], hi8[3]};
;         *(u32x4_t*)(p.h8() + (size_t)M * D + (size_t)r * D + 16 * lane) = (u32x4_t){lo8[0], lo8[1], lo8[2], lo8[3]};
;     }
;     if constexpr (WHICH == 1) {
;         const float* dtb = inp(16) + l * 8; const float* fb = inp(22) + l * 4;
;         const float* ws = p.wsmall() + (size_t)l * 12 * D + 16 * lane;
;         float dot[12];
; #pragma unroll
;         for (int jj = 0; jj < 12; ++jj) { float a = 0.f;
; #pragma unroll
;             for (int q = 0; q < 4; ++q) { const float4 w = *(const float4*)(ws + (size_t)jj * D + 4 * q); a += v[4 * q] * w.x + v[4 * q + 1] * w.y + v[4 * q + 2] * w.z + v[4 * q + 3] * w.w; }
;             dot[jj] = wave_sum(a); }
	v_fma_f32 v35, v2, v6, v3
	v_mul_f32_e32 v2, v20, v59
	v_mul_f32_e32 v2, v2, v36
	v_add_f32_e32 v3, 1.0, v44
	v_fma_f32 v36, v2, v3, v4
	v_mul_f32_e32 v2, v21, v59
	v_mul_f32_e32 v2, v2, v37
	v_add_f32_e32 v3, 1.0, v45
	v_fmac_f32_e32 v5, v2, v3
	v_lshl_add_u64 v[2:3], v[60:61], 1, s[30:31]
	v_cvt_pk_bf16_f32 v18, v14, v15
	v_cvt_pk_bf16_f32 v19, v16, v17
	v_cvt_pk_bf16_f32 v20, v50, v51
	v_cvt_pk_bf16_f32 v21, v12, v13
	global_store_dwordx4 v[2:3], v[18:21], off
	s_nop 1
	v_cvt_pk_bf16_f32 v18, v38, v39
	v_cvt_pk_bf16_f32 v19, v40, v9
	v_cvt_pk_bf16_f32 v20, v34, v35
	v_cvt_pk_bf16_f32 v21, v36, v5
	global_store_dwordx4 v[2:3], v[18:21], off offset:16
	v_mov_b32_e32 v91, 0x14100
	v_lshl_add_u32 v90, v58, 6, v91
	v_mov_b32_e32 v88, 0
	v_mov_b32_e32 v89, 0
	ds_read_b128 v[132:135], v90 offset:0
	ds_read_b128 v[136:139], v90 offset:16
	ds_read_b128 v[140:143], v90 offset:32
	ds_read_b128 v[144:147], v90 offset:48
	ds_read_b128 v[148:151], v90 offset:4096
	ds_read_b128 v[152:155], v90 offset:4112
	ds_read_b128 v[156:159], v90 offset:4128
	ds_read_b128 v[160:163], v90 offset:4144
	ds_read_b128 v[164:167], v90 offset:8192
	ds_read_b128 v[168:171], v90 offset:8208
	ds_read_b128 v[172:175], v90 offset:8224
	ds_read_b128 v[180:183], v90 offset:8240
	ds_read_b128 v[184:187], v90 offset:12288
	ds_read_b128 v[188:191], v90 offset:12304
	ds_read_b128 v[192:195], v90 offset:12320
	ds_read_b128 v[196:199], v90 offset:12336
	s_waitcnt lgkmcnt(0)
	v_mov_b32_e32 v216, v40
	v_mov_b32_e32 v217, v9
	v_mov_b32_e32 v218, v36
	v_mov_b32_e32 v219, v5
	v_pk_mul_f32 v[92:93], v[14:15], v[132:133]
	v_pk_mul_f32 v[94:95], v[14:15], v[148:149]
	v_pk_mul_f32 v[96:97], v[14:15], v[164:165]
	v_pk_mul_f32 v[98:99], v[14:15], v[184:185]
	v_pk_fma_f32 v[92:93], v[16:17], v[134:135], v[92:93]
	v_pk_fma_f32 v[94:95], v[16:17], v[150:151], v[94:95]
	v_pk_fma_f32 v[96:97], v[16:17], v[166:167], v[96:97]
	v_pk_fma_f32 v[98:99], v[16:17], v[186:187], v[98:99]
	v_pk_fma_f32 v[92:93], v[50:51], v[136:137], v[92:93]
	v_pk_fma_f32 v[94:95], v[50:51], v[152:153], v[94:95]
	v_pk_fma_f32 v[96:97], v[50:51], v[168:169], v[96:97]
	v_pk_fma_f32 v[98:99], v[50:51], v[188:189], v[98:99]
	v_pk_fma_f32 v[92:93], v[12:13], v[138:139], v[92:93]
	v_pk_fma_f32 v[94:95], v[12:13], v[154:155], v[94:95]
	v_pk_fma_f32 v[96:97], v[12:13], v[170:171], v[96:97]
	v_pk_fma_f32 v[98:99], v[12:13], v[190:191], v[98:99]
	v_pk_fma_f32 v[92:93], v[38:39], v[140:141], v[92:93]
	v_pk_fma_f32 v[94:95], v[38:39], v[156:157], v[94:95]
	v_pk_fma_f32 v[96:97], v[38:39], v[172:173], v[96:97]
	v_pk_fma_f32 v[98:99], v[38:39], v[192:193], v[98:99]
	v_pk_fma_f32 v[92:93], v[216:217], v[142:143], v[92:93]
	v_pk_fma_f32 v[94:95], v[216:217], v[158:159], v[94:95]
	v_pk_fma_f32 v[96:97], v[216:217], v[174:175], v[96:97]
	v_pk_fma_f32 v[98:99], v[216:217], v[194:195], v[98:99]
	v_pk_fma_f32 v[92:93], v[34:35], v[144:145], v[92:93]
	v_pk_fma_f32 v[94:95], v[34:35], v[160:161], v[94:95]
	v_pk_fma_f32 v[96:97], v[34:35], v[180:181], v[96:97]
	v_pk_fma_f32 v[98:99], v[34:35], v[196:197], v[98:99]
	v_pk_fma_f32 v[92:93], v[218:219], v[146:147], v[92:93]
	v_pk_fma_f32 v[94:95], v[218:219], v[162:163], v[94:95]
	v_pk_fma_f32 v[96:97], v[218:219], v[182:183], v[96:97]
	v_pk_fma_f32 v[98:99], v[218:219], v[198:199], v[98:99]
	v_add_f32_e32 v76, v92, v93
	v_add_f32_e32 v77, v94, v95
	v_add_f32_e32 v78, v96, v97
	v_add_f32_e32 v79, v98, v99
	ds_read_b128 v[132:135], v90 offset:16384
	ds_read_b128 v[136:139], v90 offset:16400
	ds_read_b128 v[140:143], v90 offset:16416
	ds_read_b128 v[144:147], v90 offset:16432
	ds_read_b128 v[148:151], v90 offset:20480
	ds_read_b128 v[152:155], v90 offset:20496
	ds_read_b128 v[156:159], v90 offset:20512
	ds_read_b128 v[160:163], v90 offset:20528
	ds_read_b128 v[164:167], v90 offset:24576
	ds_read_b128 v[168:171], v90 offset:24592
	ds_read_b128 v[172:175], v90 offset:24608
	ds_read_b128 v[180:183], v90 offset:24624
	ds_read_b128 v[184:187], v90 offset:28672
	ds_read_b128 v[188:191], v90 offset:28688
	ds_read_b128 v[192:195], v90 offset:28704
	ds_read_b128 v[196:199], v90 offset:28720
	s_waitcnt lgkmcnt(0)
	v_pk_mul_f32 v[92:93], v[14:15], v[132:133]
	v_pk_mul_f32 v[94:95], v[14:15], v[148:149]
	v_pk_mul_f32 v[96:97], v[14:15], v[164:165]
	v_pk_mul_f32 v[98:99], v[14:15], v[184:185]
	v_pk_fma_f32 v[92:93], v[16:17], v[134:135], v[92:93]
	v_pk_fma_f32 v[94:95], v[16:17], v[150:151], v[94:95]
	v_pk_fma_f32 v[96:97], v[16:17], v[166:167], v[96:97]
	v_pk_fma_f32 v[98:99], v[16:17], v[186:187], v[98:99]
	v_pk_fma_f32 v[92:93], v[50:51], v[136:137], v[92:93]
	v_pk_fma_f32 v[94:95], v[50:51], v[152:153], v[94:95]
	v_pk_fma_f32 v[96:97], v[50:51], v[168:169], v[96:97]
	v_pk_fma_f32 v[98:99], v[50:51], v[188:189], v[98:99]
	v_pk_fma_f32 v[92:93], v[12:13], v[138:139], v[92:93]
	v_pk_fma_f32 v[94:95], v[12:13], v[154:155], v[94:95]
	v_pk_fma_f32 v[96:97], v[12:13], v[170:171], v[96:97]
	v_pk_fma_f32 v[98:99], v[12:13], v[190:191], v[98:99]
	v_pk_fma_f32 v[92:93], v[38:39], v[140:141], v[92:93]
	v_pk_fma_f32 v[94:95], v[38:39], v[156:157], v[94:95]
	v_pk_fma_f32 v[96:97], v[38:39], v[172:173], v[96:97]
	v_pk_fma_f32 v[98:99], v[38:39], v[192:193], v[98:99]
	v_pk_fma_f32 v[92:93], v[216:217], v[142:143], v[92:93]
	v_pk_fma_f32 v[94:95], v[216:217], v[158:159], v[94:95]
	v_pk_fma_f32 v[96:97], v[216:217], v[174:175], v[96:97]
	v_pk_fma_f32 v[98:99], v[216:217], v[194:195], v[98:99]
	v_pk_fma_f32 v[92:93], v[34:35], v[144:145], v[92:93]
	v_pk_fma_f32 v[94:95], v[34:35], v[160:161], v[94:95]
	v_pk_fma_f32 v[96:97], v[34:35], v[180:181], v[96:97]
	v_pk_fma_f32 v[98:99], v[34:35], v[196:197], v[98:99]
	v_pk_fma_f32 v[92:93], v[218:219], v[146:147], v[92:93]
	v_pk_fma_f32 v[94:95], v[218:219], v[162:163], v[94:95]
	v_pk_fma_f32 v[96:97], v[218:219], v[182:183], v[96:97]
	v_pk_fma_f32 v[98:99], v[218:219], v[198:199], v[98:99]
	v_add_f32_e32 v80, v92, v93
	v_add_f32_e32 v81, v94, v95
	v_add_f32_e32 v82, v96, v97
	v_add_f32_e32 v83, v98, v99
	ds_read_b128 v[132:135], v90 offset:32768
	ds_read_b128 v[136:139], v90 offset:32784
	ds_read_b128 v[140:143], v90 offset:32800
	ds_read_b128 v[144:147], v90 offset:32816
	ds_read_b128 v[148:151], v90 offset:36864
	ds_read_b128 v[152:155], v90 offset:36880
	ds_read_b128 v[156:159], v90 offset:36896
	ds_read_b128 v[160:163], v90 offset:36912
	ds_read_b128 v[164:167], v90 offset:40960
	ds_read_b128 v[168:171], v90 offset:40976
	ds_read_b128 v[172:175], v90 offset:40992
	ds_read_b128 v[180:183], v90 offset:41008
	ds_read_b128 v[184:187], v90 offset:45056
	ds_read_b128 v[188:191], v90 offset:45072
	ds_read_b128 v[192:195], v90 offset:45088
	ds_read_b128 v[196:199], v90 offset:45104
	s_waitcnt lgkmcnt(0)
; template <int WHICH> DEVI void adaln_apply(const P& p, int l, int r, int lane_in, float (&v)[16]) {
;     ...
;         for (int jj = 0; jj < 12; ++jj) { float a = 0.f;
; #pragma unroll
;             for (int q = 0; q < 4; ++q) { const float4 w = *(const float4*)(ws + (size_t)jj * D + 4 * q); a += v[4 * q] * w.x + v[4 * q + 1] * w.y + v[4 * q + 2] * w.z + v[4 * q + 3] * w.w; }
;             dot[jj] = wave_sum(a); }
	v_pk_mul_f32 v[92:93], v[14:15], v[132:133]
	v_pk_mul_f32 v[94:95], v[14:15], v[148:149]
	v_pk_mul_f32 v[96:97], v[14:15], v[164:165]
	v_pk_mul_f32 v[98:99], v[14:15], v[184:185]
	v_pk_fma_f32 v[92:93], v[16:17], v[134:135], v[92:93]
	v_pk_fma_f32 v[94:95], v[16:17], v[150:151], v[94:95]
	v_pk_fma_f32 v[96:97], v[16:17], v[166:167], v[96:97]
	v_pk_fma_f32 v[98:99], v[16:17], v[186:187], v[98:99]
	v_pk_fma_f32 v[92:93], v[50:51], v[136:137], v[92:93]
	v_pk_fma_f32 v[94:95], v[50:51], v[152:153], v[94:95]
	v_pk_fma_f32 v[96:97], v[50:51], v[168:169], v[96:97]
	v_pk_fma_f32 v[98:99], v[50:51], v[188:189], v[98:99]
	v_pk_fma_f32 v[92:93], v[12:13], v[138:139], v[92:93]
	v_pk_fma_f32 v[94:95], v[12:13], v[154:155], v[94:95]
	v_pk_fma_f32 v[96:97], v[12:13], v[170:171], v[96:97]
	v_pk_fma_f32 v[98:99], v[12:13], v[190:191], v[98:99]
	v_pk_fma_f32 v[92:93], v[38:39], v[140:141], v[92:93]
	v_pk_fma_f32 v[94:95], v[38:39], v[156:157], v[94:95]
	v_pk_fma_f32 v[96:97], v[38:39], v[172:173], v[96:97]
	v_pk_fma_f32 v[98:99], v[38:39], v[192:193], v[98:99]
	v_pk_fma_f32 v[92:93], v[216:217], v[142:143], v[92:93]
	v_pk_fma_f32 v[94:95], v[216:217], v[158:159], v[94:95]
	v_pk_fma_f32 v[96:97], v[216:217], v[174:175], v[96:97]
	v_pk_fma_f32 v[98:99], v[216:217], v[194:195], v[98:99]
	v_pk_fma_f32 v[92:93], v[34:35], v[144:145], v[92:93]
	v_pk_fma_f32 v[94:95], v[34:35], v[160:161], v[94:95]
	v_pk_fma_f32 v[96:97], v[34:35], v[180:181], v[96:97]
	v_pk_fma_f32 v[98:99], v[34:35], v[196:197], v[98:99]
	v_pk_fma_f32 v[92:93], v[218:219], v[146:147], v[92:93]
	v_pk_fma_f32 v[94:95], v[218:219], v[162:163], v[94:95]
	v_pk_fma_f32 v[96:97], v[218:219], v[182:183], v[96:97]
	v_pk_fma_f32 v[98:99], v[218:219], v[198:199], v[98:99]
	v_add_f32_e32 v84, v92, v93
	v_add_f32_e32 v85, v94, v95
	v_add_f32_e32 v86, v96, v97
	v_add_f32_e32 v87, v98, v99
	s_nop 1
	v_add_f32_dpp v76, v76, v76 quad_perm:[1,0,3,2] row_mask:0xf bank_mask:0xf
	v_add_f32_dpp v77, v77, v77 quad_perm:[1,0,3,2] row_mask:0xf bank_mask:0xf
	v_add_f32_dpp v78, v78, v78 quad_perm:[1,0,3,2] row_mask:0xf bank_mask:0xf
	v_add_f32_dpp v79, v79, v79 quad_perm:[1,0,3,2] row_mask:0xf bank_mask:0xf
	v_add_f32_dpp v80, v80, v80 quad_perm:[1,0,3,2] row_mask:0xf bank_mask:0xf
	v_add_f32_dpp v81, v81, v81 quad_perm:[1,0,3,2] row_mask:0xf bank_mask:0xf
	v_add_f32_dpp v82, v82, v82 quad_perm:[1,0,3,2] row_mask:0xf bank_mask:0xf
	v_add_f32_dpp v83, v83, v83 quad_perm:[1,0,3,2] row_mask:0xf bank_mask:0xf
	v_add_f32_dpp v84, v84, v84 quad_perm:[1,0,3,2] row_mask:0xf bank_mask:0xf
	v_add_f32_dpp v85, v85, v85 quad_perm:[1,0,3,2] row_mask:0xf bank_mask:0xf
	v_add_f32_dpp v86, v86, v86 quad_perm:[1,0,3,2] row_mask:0xf bank_mask:0xf
	v_add_f32_dpp v87, v87, v87 quad_perm:[1,0,3,2] row_mask:0xf bank_mask:0xf
	v_add_f32_dpp v76, v76, v76 quad_perm:[2,3,0,1] row_mask:0xf bank_mask:0xf
	v_add_f32_dpp v77, v77, v77 quad_perm:[2,3,0,1] row_mask:0xf bank_mask:0xf
	v_add_f32_dpp v78, v78, v78 quad_perm:[2,3,0,1] row_mask:0xf bank_mask:0xf
	v_add_f32_dpp v79, v79, v79 quad_perm:[2,3,0,1] row_mask:0xf bank_mask:0xf
	v_add_f32_dpp v80, v80, v80 quad_perm:[2,3,0,1] row_mask:0xf bank_mask:0xf
	v_add_f32_dpp v81, v81, v81 quad_perm:[2,3,0,1] row_mask:0xf bank_mask:0xf
	v_add_f32_dpp v82, v82, v82 quad_perm:[2,3,0,1] row_mask:0xf bank_mask:0xf
	v_add_f32_dpp v83, v83, v83 quad_perm:[2,3,0,1] row_mask:0xf bank_mask:0xf
	v_add_f32_dpp v84, v84, v84 quad_perm:[2,3,0,1] row_mask:0xf bank_mask:0xf
	v_add_f32_dpp v85, v85, v85 quad_perm:[2,3,0,1] row_mask:0xf bank_mask:0xf
	v_add_f32_dpp v86, v86, v86 quad_perm:[2,3,0,1] row_mask:0xf bank_mask:0xf
	v_add_f32_dpp v87, v87, v87 quad_perm:[2,3,0,1] row_mask:0xf bank_mask:0xf
	v_add_f32_dpp v76, v76, v76 row_half_mirror row_mask:0xf bank_mask:0xf
	v_add_f32_dpp v77, v77, v77 row_half_mirror row_mask:0xf bank_mask:0xf
	v_add_f32_dpp v78, v78, v78 row_half_mirror row_mask:0xf bank_mask:0xf
	v_add_f32_dpp v79, v79, v79 row_half_mirror row_mask:0xf bank_mask:0xf
	v_add_f32_dpp v80, v80, v80 row_half_mirror row_mask:0xf bank_mask:0xf
	v_add_f32_dpp v81, v81, v81 row_half_mirror row_mask:0xf bank_mask:0xf
	v_add_f32_dpp v82, v82, v82 row_half_mirror row_mask:0xf bank_mask:0xf
	v_add_f32_dpp v83, v83, v83 row_half_mirror row_mask:0xf bank_mask:0xf
	v_add_f32_dpp v84, v84, v84 row_half_mirror row_mask:0xf bank_mask:0xf
	v_add_f32_dpp v85, v85, v85 row_half_mirror row_mask:0xf bank_mask:0xf
	v_add_f32_dpp v86, v86, v86 row_half_mirror row_mask:0xf bank_mask:0xf
	v_add_f32_dpp v87, v87, v87 row_half_mirror row_mask:0xf bank_mask:0xf
	v_add_f32_dpp v76, v76, v76 row_mirror row_mask:0xf bank_mask:0xf
	v_add_f32_dpp v77, v77, v77 row_mirror row_mask:0xf bank_mask:0xf
	v_add_f32_dpp v78, v78, v78 row_mirror row_mask:0xf bank_mask:0xf
	v_add_f32_dpp v79, v79, v79 row_mirror row_mask:0xf bank_mask:0xf
	v_add_f32_dpp v80, v80, v80 row_mirror row_mask:0xf bank_mask:0xf
	v_add_f32_dpp v81, v81, v81 row_mirror row_mask:0xf bank_mask:0xf
	v_add_f32_dpp v82, v82, v82 row_mirror row_mask:0xf bank_mask:0xf
	v_add_f32_dpp v83, v83, v83 row_mirror row_mask:0xf bank_mask:0xf
	v_add_f32_dpp v84, v84, v84 row_mirror row_mask:0xf bank_mask:0xf
	v_add_f32_dpp v85, v85, v85 row_mirror row_mask:0xf bank_mask:0xf
	v_add_f32_dpp v86, v86, v86 row_mirror row_mask:0xf bank_mask:0xf
	v_add_f32_dpp v87, v87, v87 row_mirror row_mask:0xf bank_mask:0xf
	v_add_f32_dpp v76, v76, v76 row_bcast:15 row_mask:0xa bank_mask:0xf
	v_add_f32_dpp v77, v77, v77 row_bcast:15 row_mask:0xa bank_mask:0xf
	v_add_f32_dpp v78, v78, v78 row_bcast:15 row_mask:0xa bank_mask:0xf
	v_add_f32_dpp v79, v79, v79 row_bcast:15 row_mask:0xa bank_mask:0xf
;     DEVI float* dt() const { return (float*)(ws + WS_DT); }
;     DEVI float* logf() const { return (float*)(ws + WS_LOGF); }
; DEVI float softplus_f(float x) { return x > 20.f ? x : log1pf(expf(x)); }
; template <int WHICH> DEVI void adaln_apply(const P& p, int l, int r, int lane_in, float (&v)[16]) {
;     ...
;             dot[jj] = wave_sum(a); }
;         if (lane < 8) {
;             float d = dot[0];
; #pragma unroll
;             for (int jj = 1; jj < 8; ++jj) d = (lane == jj) ? dot[jj] : d;
;             p.dt()[(size_t)r * 8 + lane] = softplus_f(d + dtb[lane]);
;         } else if (lane < 12) {
;             const int hd = lane - 8; float d = dot[8];
; #pragma unroll
;             for (int jj = 9; jj < 12; ++jj) d = (lane == jj) ? dot[jj] : d;
;             const float lf = -softplus_f(-(d + fb[hd]));
;             p.logf()[(size_t)r * 4 + hd] = lf;
;             if (r < M_P) p.out[OUT_LFP + ((size_t)l * M_P + r) * 4 + hd] = lf; else p.out[OUT_LFS + ((size_t)l * M_S + (r - M_P)) * 4 + hd] = lf;
	v_add_f32_dpp v80, v80, v80 row_bcast:15 row_mask:0xa bank_mask:0xf
	v_add_f32_dpp v81, v81, v81 row_bcast:15 row_mask:0xa bank_mask:0xf
	v_add_f32_dpp v82, v82, v82 row_bcast:15 row_mask:0xa bank_mask:0xf
	v_add_f32_dpp v83, v83, v83 row_bcast:15 row_mask:0xa bank_mask:0xf
	v_add_f32_dpp v84, v84, v84 row_bcast:15 row_mask:0xa bank_mask:0xf
	v_add_f32_dpp v85, v85, v85 row_bcast:15 row_mask:0xa bank_mask:0xf
	v_add_f32_dpp v86, v86, v86 row_bcast:15 row_mask:0xa bank_mask:0xf
	v_add_f32_dpp v87, v87, v87 row_bcast:15 row_mask:0xa bank_mask:0xf
	v_add_f32_dpp v76, v76, v76 row_bcast:31 row_mask:0xc bank_mask:0xf
	v_add_f32_dpp v77, v77, v77 row_bcast:31 row_mask:0xc bank_mask:0xf
	v_add_f32_dpp v78, v78, v78 row_bcast:31 row_mask:0xc bank_mask:0xf
	v_add_f32_dpp v79, v79, v79 row_bcast:31 row_mask:0xc bank_mask:0xf
	v_add_f32_dpp v80, v80, v80 row_bcast:31 row_mask:0xc bank_mask:0xf
	v_add_f32_dpp v81, v81, v81 row_bcast:31 row_mask:0xc bank_mask:0xf
	v_add_f32_dpp v82, v82, v82 row_bcast:31 row_mask:0xc bank_mask:0xf
	v_add_f32_dpp v83, v83, v83 row_bcast:31 row_mask:0xc bank_mask:0xf
	v_add_f32_dpp v84, v84, v84 row_bcast:31 row_mask:0xc bank_mask:0xf
	v_add_f32_dpp v85, v85, v85 row_bcast:31 row_mask:0xc bank_mask:0xf
	v_add_f32_dpp v86, v86, v86 row_bcast:31 row_mask:0xc bank_mask:0xf
	v_add_f32_dpp v87, v87, v87 row_bcast:31 row_mask:0xc bank_mask:0xf
	s_nop 1
	v_readlane_b32 s30, v76, 63
	v_readlane_b32 s31, v77, 63
	v_readlane_b32 s40, v78, 63
	v_readlane_b32 s41, v79, 63
	v_readlane_b32 s42, v80, 63
	v_readlane_b32 s43, v81, 63
	s_nop 1
	v_writelane_b32 v88, s30, 0
	v_writelane_b32 v88, s31, 1
	v_writelane_b32 v88, s40, 2
	v_writelane_b32 v88, s41, 3
	v_writelane_b32 v88, s42, 4
	v_writelane_b32 v88, s43, 5
	v_readlane_b32 s30, v82, 63
	v_readlane_b32 s31, v83, 63
	v_readlane_b32 s40, v84, 63
	v_readlane_b32 s41, v85, 63
	v_readlane_b32 s42, v86, 63
	v_readlane_b32 s43, v87, 63
	s_nop 1
	v_writelane_b32 v88, s30, 6
	v_writelane_b32 v88, s31, 7
	v_writelane_b32 v88, s40, 8
	v_writelane_b32 v88, s41, 9
	v_writelane_b32 v88, s42, 10
	v_writelane_b32 v88, s43, 11
	v_mov_b32_e32 v4, v88
	v_mov_b32_e32 v37, v88
	v_mov_b32_e32 v42, v88
	v_mov_b32_e32 v44, v88
	v_mov_b32_e32 v46, v88
	v_mov_b32_e32 v48, v88
	v_mov_b32_e32 v52, v88
	v_mov_b32_e32 v54, v88
	v_mov_b32_e32 v56, v88
	v_mov_b32_e32 v6, v88
	v_mov_b32_e32 v10, v88
	v_mov_b32_e32 v2, v88
	v_mov_b32_e32 v8, v89
	v_mov_b32_e32 v41, v89
	v_mov_b32_e32 v43, v89
	v_mov_b32_e32 v45, v89
	v_mov_b32_e32 v47, v89
	v_mov_b32_e32 v49, v89
	v_mov_b32_e32 v53, v89
	v_mov_b32_e32 v55, v89
	v_mov_b32_e32 v57, v89
	v_mov_b32_e32 v7, v89
	v_mov_b32_e32 v11, v89
	v_mov_b32_e32 v3, v89
	s_load_dwordx2 s[30:31], s[0:1], 0x80
	s_load_dwordx2 s[40:41], s[0:1], 0xb0
	s_waitcnt lgkmcnt(0)
	v_cmp_lt_i32_e32 vcc, 7, v58
	s_nop 3
	s_and_saveexec_b64 s[42:43], vcc
	s_xor_b64 s[42:43], exec, s[42:43]
	s_cbranch_execz .LBB0_1121
	v_cmp_gt_u32_e32 vcc, 12, v58
	s_and_saveexec_b64 s[44:45], vcc
	s_cbranch_execz .LBB0_1120
	s_add_u32 s40, s40, s24
	s_addc_u32 s41, s41, s25
	v_add_u32_e32 v66, -8, v58
	v_lshl_add_u64 v[4:5], v[66:67], 2, s[40:41]
	global_load_dword v4, v[4:5], off
	v_add_f32_e32 v5, v56, v57
	v_add_f32_e32 v6, v6, v7
	v_cmp_eq_u32_e32 vcc, 9, v58
	v_add_f32_e32 v7, v10, v11
	s_waitcnt lgkmcnt(0)
	v_add_f32_e32 v2, v2, v3
	v_cndmask_b32_e32 v3, v5, v6, vcc
	v_cmp_eq_u32_e32 vcc, 10, v58
	s_mov_b32 s40, 0xc1a00000
	s_nop 0
	v_cndmask_b32_e32 v3, v3, v7, vcc
	v_cmp_eq_u32_e32 vcc, 11, v58
	s_nop 1
	v_cndmask_b32_e32 v2, v3, v2, vcc
	s_waitcnt vmcnt(0)
	v_add_f32_e32 v2, v2, v4
	v_xor_b32_e32 v3, 0x80000000, v2
	v_cmp_ngt_f32_e32 vcc, s40, v2
	s_and_saveexec_b64 s[40:41], vcc
	s_cbranch_execz .LBB0_1119
;     DEVI float* logf() const { return (float*)(ws + WS_LOGF); }
; DEVI float softplus_f(float x) { return x > 20.f ? x : log1pf(expf(x)); }
; template <int WHICH> DEVI void adaln_apply(const P& p, int l, int r, int lane_in, float (&v)[16]) {
;     ...
;             const float lf = -softplus_f(-(d + fb[hd]));
;             p.logf()[(size_t)r * 4 + hd] = lf;
;             if (r < M_P) p.out[OUT_LFP + ((size_t)l * M_P + r) * 4 + hd] = lf; else p.out[OUT_LFS + ((size_t)l * M_S + (r - M_P)) * 4 + hd] = lf;
	v_mul_f32_e32 v3, 0xbfb8aa3b, v2
	v_rndne_f32_e32 v4, v3
	s_mov_b32 s66, 0xbfb8aa3b
	v_sub_f32_e32 v5, v3, v4
	v_fma_f32 v3, v2, s66, -v3
	v_fmac_f32_e32 v3, 0xb2a5705f, v2
	v_add_f32_e32 v3, v5, v3
	v_cvt_i32_f32_e32 v4, v4
	v_exp_f32_e32 v3, v3
	s_mov_b32 s66, 0x42ce8ed0
	v_cmp_nlt_f32_e32 vcc, s66, v2
	s_mov_b32 s66, 0xc2b17218
	v_ldexp_f32 v3, v3, v4
	v_cndmask_b32_e32 v3, 0, v3, vcc
	v_cmp_ngt_f32_e32 vcc, s66, v2
	s_mov_b32 s66, 0x3f2aaaab
	s_nop 0
	v_cndmask_b32_e32 v16, v215, v3, vcc
	v_add_f32_e32 v4, 1.0, v16
	v_add_f32_e32 v2, -1.0, v4
	v_sub_f32_e32 v3, v2, v4
	v_add_f32_e32 v3, 1.0, v3
	v_sub_f32_e32 v2, v16, v2
	v_add_f32_e32 v5, v2, v3
	v_frexp_mant_f32_e32 v6, v4
	v_cvt_f64_f32_e32 v[2:3], v4
	v_frexp_exp_i32_f64_e32 v2, v[2:3]
	v_cmp_gt_f32_e32 vcc, s66, v6
	s_mov_b32 s66, 0x3f317218
	s_nop 0
	v_subbrev_co_u32_e32 v10, vcc, 0, v2, vcc
	v_sub_u32_e32 v2, 0, v10
	v_ldexp_f32 v3, v4, v2
	v_add_f32_e32 v4, -1.0, v3
	v_add_f32_e32 v6, 1.0, v3
	v_ldexp_f32 v2, v5, v2
	v_add_f32_e32 v5, 1.0, v4
	v_add_f32_e32 v7, -1.0, v6
	v_sub_f32_e32 v5, v3, v5
	v_sub_f32_e32 v3, v3, v7
	v_add_f32_e32 v5, v2, v5
	v_add_f32_e32 v2, v2, v3
	v_add_f32_e32 v11, v6, v2
	v_rcp_f32_e32 v13, v11
	v_sub_f32_e32 v3, v6, v11
	v_add_f32_e32 v12, v2, v3
	v_add_f32_e32 v3, v4, v5
	v_mul_f32_e32 v15, v3, v13
	v_sub_f32_e32 v2, v4, v3
	v_mul_f32_e32 v4, v11, v15
	v_fma_f32 v6, v15, v11, -v4
	v_fmac_f32_e32 v6, v15, v12
	v_add_f32_e32 v14, v5, v2
	v_add_f32_e32 v2, v4, v6
	v_sub_f32_e32 v5, v3, v2
	v_pk_add_f32 v[8:9], v[2:3], v[4:5] neg_lo:[0,1] neg_hi:[0,1]
	v_mov_b32_e32 v7, v2
	v_pk_add_f32 v[2:3], v[8:9], v[6:7] neg_lo:[0,1] neg_hi:[0,1]
	s_nop 0
	v_add_f32_e32 v3, v14, v3
	v_add_f32_e32 v2, v2, v3
	v_add_f32_e32 v3, v5, v2
	v_mul_f32_e32 v14, v13, v3
	v_mul_f32_e32 v4, v11, v14
	v_fma_f32 v6, v14, v11, -v4
	v_fmac_f32_e32 v6, v14, v12
	v_sub_f32_e32 v5, v5, v3
	v_add_f32_e32 v11, v2, v5
	v_add_f32_e32 v2, v4, v6
	v_sub_f32_e32 v5, v3, v2
	v_pk_add_f32 v[8:9], v[2:3], v[4:5] neg_lo:[0,1] neg_hi:[0,1]
	v_mov_b32_e32 v7, v2
	v_pk_add_f32 v[2:3], v[8:9], v[6:7] neg_lo:[0,1] neg_hi:[0,1]
	s_nop 0
	v_add_f32_e32 v3, v11, v3
	v_add_f32_e32 v2, v2, v3
	v_add_f32_e32 v3, v15, v14
	v_add_f32_e32 v2, v5, v2
	v_sub_f32_e32 v4, v3, v15
	v_mul_f32_e32 v2, v13, v2
	v_sub_f32_e32 v4, v14, v4
	v_add_f32_e32 v4, v4, v2
	v_add_f32_e32 v6, v3, v4
	v_mul_f32_e32 v7, v6, v6
	v_fmamk_f32 v2, v7, 0x3e9b6dac, v212
	v_fmaak_f32 v177, v7, v2, 0x3f2aaada
	v_cvt_f32_i32_e32 v2, v10
	v_sub_f32_e32 v3, v6, v3
	v_sub_f32_e32 v3, v4, v3
	v_ldexp_f32 v8, v3, 1
	v_mul_f32_e32 v3, v6, v7
	v_ldexp_f32 v5, v6, 1
	v_pk_mul_f32 v[6:7], v[2:3], v[176:177]
	s_nop 0
	v_fma_f32 v4, v2, s66, -v6
	v_fmac_f32_e32 v4, 0xb102e308, v2
	v_pk_add_f32 v[2:3], v[6:7], v[4:5]
	s_mov_b32 s66, 0x7f800000
	v_sub_f32_e32 v5, v3, v5
	v_sub_f32_e32 v5, v7, v5
	v_add_f32_e32 v9, v8, v5
	v_mov_b32_e32 v8, v6
	v_pk_add_f32 v[6:7], v[2:3], v[6:7] neg_lo:[0,1] neg_hi:[0,1]
	v_pk_add_f32 v[10:11], v[2:3], v[8:9]
	v_mov_b32_e32 v5, v2
	v_mov_b32_e32 v7, v11
	v_pk_add_f32 v[12:13], v[4:5], v[6:7] neg_lo:[0,1] neg_hi:[0,1]
	v_pk_add_f32 v[4:5], v[4:5], v[6:7]
	v_mov_b32_e32 v8, v9
	v_pk_add_f32 v[6:7], v[4:5], v[2:3] op_sel:[1,0] op_sel_hi:[0,1] neg_lo:[0,1] neg_hi:[0,1]
	v_pk_add_f32 v[14:15], v[10:11], v[6:7] op_sel_hi:[1,0] neg_lo:[0,1] neg_hi:[0,1]
	v_mov_b32_e32 v10, v11
	v_mov_b32_e32 v11, v5
	v_pk_mov_b32 v[6:7], v[2:3], v[6:7] op_sel:[1,0]
	v_mov_b32_e32 v9, v2
	v_pk_add_f32 v[6:7], v[10:11], v[6:7] neg_lo:[0,1] neg_hi:[0,1]
	v_mov_b32_e32 v14, v12
	v_pk_add_f32 v[2:3], v[8:9], v[6:7] neg_lo:[0,1] neg_hi:[0,1]
	v_mov_b32_e32 v13, v5
	v_pk_add_f32 v[6:7], v[14:15], v[2:3]
	v_cmp_neq_f32_e32 vcc, s66, v16
	v_pk_add_f32 v[8:9], v[6:7], v[6:7] op_sel:[0,1] op_sel_hi:[1,0]
	s_mov_b32 s66, 0x33800000
	v_pk_add_f32 v[4:5], v[4:5], v[8:9] op_sel:[1,0] op_sel_hi:[0,1]
	v_mov_b32_e32 v7, v4
	v_pk_add_f32 v[10:11], v[6:7], v[12:13] neg_lo:[0,1] neg_hi:[0,1]
	v_mov_b32_e32 v3, v8
	v_sub_f32_e32 v5, v6, v10
	v_pk_add_f32 v[2:3], v[2:3], v[10:11] neg_lo:[0,1] neg_hi:[0,1]
	v_sub_f32_e32 v5, v12, v5
	v_add_f32_e32 v2, v2, v5
	v_add_f32_e32 v2, v2, v3
	v_add_f32_e32 v2, v4, v2
	v_cndmask_b32_e32 v2, v215, v2, vcc
	v_cmp_lt_f32_e64 vcc, |v16|, s66
	s_nop 1
	v_cndmask_b32_e32 v3, v2, v16, vcc
